# v75 + loop-edge edit in the nine GEMM K-loops: counter / pointer increments and exit compare moved in front of the last load segment's wait, only the branch stays behind the last barrier
# speedup vs baseline: 1.0121x; 1.0121x over previous
.LBB0_219:
	ds_read_b128 v[148:151], v188
	ds_read_b128 v[152:155], v188 offset:1024
	ds_read_b128 v[156:159], v188 offset:2048
	ds_read_b128 v[160:163], v188 offset:3072
	ds_read_b128 v[164:167], v189
	ds_read_b128 v[168:171], v189 offset:1024
	ds_read_b128 v[172:175], v189 offset:2048
	ds_read_b128 v[176:179], v189 offset:3072
	s_add_u32 s38, s36, 0xfffc0080
	s_addc_u32 s39, s37, -1
	s_cmp_eq_u32 s64, 12
	s_cselect_b32 s41, s7, s39
	s_cselect_b32 s40, s25, s38
	s_cselect_b32 s39, s19, s63
	s_cselect_b32 s38, s33, s35
	v_lshl_add_u64 v[180:181], s[36:37], 0, v[138:139]
	s_add_i32 m0, s47, 0xc000
	ds_read_b128 v[196:199], v190
	ds_read_b128 v[202:205], v190 offset:1024
	ds_read_b128 v[206:209], v190 offset:2048
	ds_read_b128 v[210:213], v190 offset:3072
	ds_read_b128 v[214:217], v190 offset:4096
	ds_read_b128 v[218:221], v190 offset:5120
	ds_read_b128 v[222:225], v190 offset:6144
	ds_read_b128 v[226:229], v190 offset:7168
	global_load_lds_dwordx4 v[180:181], off
	v_lshl_add_u64 v[180:181], s[36:37], 0, v[140:141]
	s_add_i32 m0, s47, 0xe000
	s_nop 0
	global_load_lds_dwordx4 v[180:181], off
	s_waitcnt vmcnt(8)
	s_waitcnt lgkmcnt(0)
	s_barrier
	s_setprio 1
	s_waitcnt lgkmcnt(0)
	v_mfma_f32_16x16x32_bf16 v[124:127], v[148:151], v[196:199], v[124:127]
	v_mfma_f32_16x16x32_bf16 v[120:123], v[156:159], v[196:199], v[120:123]
	v_mfma_f32_16x16x32_bf16 v[116:119], v[148:151], v[206:209], v[116:119]
	v_mfma_f32_16x16x32_bf16 v[108:111], v[156:159], v[206:209], v[108:111]
	v_mfma_f32_16x16x32_bf16 v[100:103], v[148:151], v[214:217], v[100:103]
	v_mfma_f32_16x16x32_bf16 v[92:95], v[156:159], v[214:217], v[92:95]
	v_mfma_f32_16x16x32_bf16 v[84:87], v[148:151], v[222:225], v[84:87]
	v_mfma_f32_16x16x32_bf16 v[76:79], v[156:159], v[222:225], v[76:79]
	v_mfma_f32_16x16x32_bf16 v[124:127], v[152:155], v[202:205], v[124:127]
	v_mfma_f32_16x16x32_bf16 v[120:123], v[160:163], v[202:205], v[120:123]
	v_mfma_f32_16x16x32_bf16 v[116:119], v[152:155], v[210:213], v[116:119]
	v_mfma_f32_16x16x32_bf16 v[108:111], v[160:163], v[210:213], v[108:111]
	v_mfma_f32_16x16x32_bf16 v[100:103], v[152:155], v[218:221], v[100:103]
	v_mfma_f32_16x16x32_bf16 v[92:95], v[160:163], v[218:221], v[92:95]
	v_mfma_f32_16x16x32_bf16 v[84:87], v[152:155], v[226:229], v[84:87]
	v_mfma_f32_16x16x32_bf16 v[76:79], v[160:163], v[226:229], v[76:79]
	s_setprio 0
	s_setprio 1
	v_mfma_f32_16x16x32_bf16 v[112:115], v[164:167], v[196:199], v[112:115]
	v_mfma_f32_16x16x32_bf16 v[104:107], v[172:175], v[196:199], v[104:107]
	v_mfma_f32_16x16x32_bf16 v[96:99], v[164:167], v[206:209], v[96:99]
	v_mfma_f32_16x16x32_bf16 v[88:91], v[172:175], v[206:209], v[88:91]
	v_mfma_f32_16x16x32_bf16 v[80:83], v[164:167], v[214:217], v[80:83]
	v_mfma_f32_16x16x32_bf16 v[72:75], v[172:175], v[214:217], v[72:75]
	v_mfma_f32_16x16x32_bf16 v[68:71], v[164:167], v[222:225], v[68:71]
	v_mfma_f32_16x16x32_bf16 v[64:67], v[172:175], v[222:225], v[64:67]
	v_mfma_f32_16x16x32_bf16 v[112:115], v[168:171], v[202:205], v[112:115]
	v_mfma_f32_16x16x32_bf16 v[104:107], v[176:179], v[202:205], v[104:107]
	v_mfma_f32_16x16x32_bf16 v[96:99], v[168:171], v[210:213], v[96:99]
	v_mfma_f32_16x16x32_bf16 v[88:91], v[176:179], v[210:213], v[88:91]
	v_mfma_f32_16x16x32_bf16 v[80:83], v[168:171], v[218:221], v[80:83]
	v_mfma_f32_16x16x32_bf16 v[72:75], v[176:179], v[218:221], v[72:75]
	v_mfma_f32_16x16x32_bf16 v[68:71], v[168:171], v[226:229], v[68:71]
	v_mfma_f32_16x16x32_bf16 v[64:67], v[176:179], v[226:229], v[64:67]
	s_setprio 0
	s_barrier
	s_add_i32 s65, s59, s46
	v_lshl_add_u64 v[180:181], s[38:39], 0, v[130:131]
	s_mov_b32 m0, s65
	ds_read_b128 v[196:199], v190 offset:16384
	ds_read_b128 v[202:205], v190 offset:17408
	ds_read_b128 v[206:209], v190 offset:18432
	ds_read_b128 v[210:213], v190 offset:19456
	ds_read_b128 v[214:217], v190 offset:20480
	ds_read_b128 v[218:221], v190 offset:21504
	ds_read_b128 v[222:225], v190 offset:22528
	ds_read_b128 v[226:229], v190 offset:23552
	global_load_lds_dwordx4 v[180:181], off
	s_add_i32 m0, s65, 0x2000
	s_add_u32 s66, s38, 0x40000
	v_lshl_add_u64 v[230:231], s[38:39], 0, v[134:135]
	s_addc_u32 s67, s39, 0
	s_add_i32 s65, s60, s46
	global_load_lds_dwordx4 v[230:231], off
	v_lshl_add_u64 v[232:233], s[66:67], 0, v[130:131]
	s_mov_b32 m0, s65
	v_lshl_add_u64 v[234:235], s[40:41], 0, v[132:133]
	global_load_lds_dwordx4 v[232:233], off
	v_lshl_add_u64 v[232:233], s[66:67], 0, v[134:135]
	s_add_i32 m0, s65, 0x2000
	s_nop 0
	global_load_lds_dwordx4 v[232:233], off
	v_lshl_add_u64 v[232:233], s[40:41], 0, v[128:129]
	s_mov_b32 m0, s47
	s_nop 0
	global_load_lds_dwordx4 v[232:233], off
	s_mov_b32 m0, s48
	s_nop 0
	global_load_lds_dwordx4 v[234:235], off
	s_waitcnt vmcnt(8)
	s_waitcnt lgkmcnt(0)
	s_barrier
	s_setprio 1
	s_waitcnt lgkmcnt(0)
	v_mfma_f32_16x16x32_bf16 v[60:63], v[148:151], v[196:199], v[60:63]
	v_mfma_f32_16x16x32_bf16 v[56:59], v[156:159], v[196:199], v[56:59]
	v_mfma_f32_16x16x32_bf16 v[52:55], v[148:151], v[206:209], v[52:55]
	v_mfma_f32_16x16x32_bf16 v[44:47], v[156:159], v[206:209], v[44:47]
	v_mfma_f32_16x16x32_bf16 v[36:39], v[148:151], v[214:217], v[36:39]
	v_mfma_f32_16x16x32_bf16 v[28:31], v[156:159], v[214:217], v[28:31]
	v_mfma_f32_16x16x32_bf16 v[20:23], v[148:151], v[222:225], v[20:23]
	v_mfma_f32_16x16x32_bf16 v[12:15], v[156:159], v[222:225], v[12:15]
	v_mfma_f32_16x16x32_bf16 v[60:63], v[152:155], v[202:205], v[60:63]
	v_mfma_f32_16x16x32_bf16 v[56:59], v[160:163], v[202:205], v[56:59]
	v_mfma_f32_16x16x32_bf16 v[52:55], v[152:155], v[210:213], v[52:55]
	v_mfma_f32_16x16x32_bf16 v[44:47], v[160:163], v[210:213], v[44:47]
	v_mfma_f32_16x16x32_bf16 v[36:39], v[152:155], v[218:221], v[36:39]
	v_mfma_f32_16x16x32_bf16 v[28:31], v[160:163], v[218:221], v[28:31]
	v_mfma_f32_16x16x32_bf16 v[20:23], v[152:155], v[226:229], v[20:23]
	v_mfma_f32_16x16x32_bf16 v[12:15], v[160:163], v[226:229], v[12:15]
	s_setprio 0
	s_setprio 1
	v_mfma_f32_16x16x32_bf16 v[48:51], v[164:167], v[196:199], v[48:51]
	v_mfma_f32_16x16x32_bf16 v[40:43], v[172:175], v[196:199], v[40:43]
	v_mfma_f32_16x16x32_bf16 v[32:35], v[164:167], v[206:209], v[32:35]
	v_mfma_f32_16x16x32_bf16 v[24:27], v[172:175], v[206:209], v[24:27]
	v_mfma_f32_16x16x32_bf16 v[16:19], v[164:167], v[214:217], v[16:19]
	v_mfma_f32_16x16x32_bf16 v[8:11], v[172:175], v[214:217], v[8:11]
	v_mfma_f32_16x16x32_bf16 v[4:7], v[164:167], v[222:225], v[4:7]
	v_mfma_f32_16x16x32_bf16 v[0:3], v[172:175], v[222:225], v[0:3]
	v_mfma_f32_16x16x32_bf16 v[48:51], v[168:171], v[202:205], v[48:51]
	v_mfma_f32_16x16x32_bf16 v[40:43], v[176:179], v[202:205], v[40:43]
	v_mfma_f32_16x16x32_bf16 v[32:35], v[168:171], v[210:213], v[32:35]
	v_mfma_f32_16x16x32_bf16 v[24:27], v[176:179], v[210:213], v[24:27]
	v_mfma_f32_16x16x32_bf16 v[16:19], v[168:171], v[218:221], v[16:19]
	v_mfma_f32_16x16x32_bf16 v[8:11], v[176:179], v[218:221], v[8:11]
	v_mfma_f32_16x16x32_bf16 v[4:7], v[168:171], v[226:229], v[4:7]
	v_mfma_f32_16x16x32_bf16 v[0:3], v[176:179], v[226:229], v[0:3]
	s_setprio 0
	s_barrier
	s_add_i32 s65, 0, 0x18000
	v_add_u32_e32 v147, s65, v183
	s_add_i32 s66, 0, 0x1c000
	ds_read_b128 v[148:151], v147
	ds_read_b128 v[152:155], v147 offset:1024
	ds_read_b128 v[156:159], v147 offset:2048
	ds_read_b128 v[160:163], v147 offset:3072
	v_add_u32_e32 v147, s66, v183
	ds_read_b128 v[164:167], v147
	ds_read_b128 v[168:171], v147 offset:1024
	ds_read_b128 v[172:175], v147 offset:2048
	ds_read_b128 v[176:179], v147 offset:3072
	s_add_u32 s40, s40, 0x40000
	s_addc_u32 s41, s41, 0
	s_mov_b32 m0, s49
	v_lshl_add_u64 v[236:237], s[40:41], 0, v[128:129]
	ds_read_b128 v[196:199], v190 offset:32768
	ds_read_b128 v[202:205], v190 offset:33792
	ds_read_b128 v[206:209], v190 offset:34816
	ds_read_b128 v[210:213], v190 offset:35840
	ds_read_b128 v[214:217], v190 offset:36864
	ds_read_b128 v[218:221], v190 offset:37888
	ds_read_b128 v[222:225], v190 offset:38912
	ds_read_b128 v[226:229], v190 offset:39936
	global_load_lds_dwordx4 v[236:237], off
	v_lshl_add_u64 v[236:237], s[40:41], 0, v[132:133]
	s_mov_b32 m0, s50
	s_nop 0
	global_load_lds_dwordx4 v[236:237], off
	s_waitcnt vmcnt(8)
	s_waitcnt lgkmcnt(0)
	s_barrier
	s_setprio 1
	s_waitcnt lgkmcnt(0)
	v_mfma_f32_16x16x32_bf16 v[124:127], v[148:151], v[196:199], v[124:127]
	v_mfma_f32_16x16x32_bf16 v[120:123], v[156:159], v[196:199], v[120:123]
	v_mfma_f32_16x16x32_bf16 v[116:119], v[148:151], v[206:209], v[116:119]
	v_mfma_f32_16x16x32_bf16 v[108:111], v[156:159], v[206:209], v[108:111]
	v_mfma_f32_16x16x32_bf16 v[100:103], v[148:151], v[214:217], v[100:103]
	v_mfma_f32_16x16x32_bf16 v[92:95], v[156:159], v[214:217], v[92:95]
	v_mfma_f32_16x16x32_bf16 v[84:87], v[148:151], v[222:225], v[84:87]
	v_mfma_f32_16x16x32_bf16 v[76:79], v[156:159], v[222:225], v[76:79]
	v_mfma_f32_16x16x32_bf16 v[124:127], v[152:155], v[202:205], v[124:127]
	v_mfma_f32_16x16x32_bf16 v[120:123], v[160:163], v[202:205], v[120:123]
	v_mfma_f32_16x16x32_bf16 v[116:119], v[152:155], v[210:213], v[116:119]
	v_mfma_f32_16x16x32_bf16 v[108:111], v[160:163], v[210:213], v[108:111]
	v_mfma_f32_16x16x32_bf16 v[100:103], v[152:155], v[218:221], v[100:103]
	v_mfma_f32_16x16x32_bf16 v[92:95], v[160:163], v[218:221], v[92:95]
	v_mfma_f32_16x16x32_bf16 v[84:87], v[152:155], v[226:229], v[84:87]
	v_mfma_f32_16x16x32_bf16 v[76:79], v[160:163], v[226:229], v[76:79]
	s_setprio 0
	s_setprio 1
	v_mfma_f32_16x16x32_bf16 v[112:115], v[164:167], v[196:199], v[112:115]
	v_mfma_f32_16x16x32_bf16 v[104:107], v[172:175], v[196:199], v[104:107]
	v_mfma_f32_16x16x32_bf16 v[96:99], v[164:167], v[206:209], v[96:99]
	v_mfma_f32_16x16x32_bf16 v[88:91], v[172:175], v[206:209], v[88:91]
	v_mfma_f32_16x16x32_bf16 v[80:83], v[164:167], v[214:217], v[80:83]
	v_mfma_f32_16x16x32_bf16 v[72:75], v[172:175], v[214:217], v[72:75]
	v_mfma_f32_16x16x32_bf16 v[68:71], v[164:167], v[222:225], v[68:71]
	v_mfma_f32_16x16x32_bf16 v[64:67], v[172:175], v[222:225], v[64:67]
	v_mfma_f32_16x16x32_bf16 v[112:115], v[168:171], v[202:205], v[112:115]
	v_mfma_f32_16x16x32_bf16 v[104:107], v[176:179], v[202:205], v[104:107]
	v_mfma_f32_16x16x32_bf16 v[96:99], v[168:171], v[210:213], v[96:99]
	v_mfma_f32_16x16x32_bf16 v[88:91], v[176:179], v[210:213], v[88:91]
	v_mfma_f32_16x16x32_bf16 v[80:83], v[168:171], v[218:221], v[80:83]
	v_mfma_f32_16x16x32_bf16 v[72:75], v[176:179], v[218:221], v[72:75]
	v_mfma_f32_16x16x32_bf16 v[68:71], v[168:171], v[226:229], v[68:71]
	v_mfma_f32_16x16x32_bf16 v[64:67], v[176:179], v[226:229], v[64:67]
	s_setprio 0
	s_barrier
	s_add_i32 s40, s65, s46
	v_lshl_add_u64 v[180:181], v[180:181], 0, s[14:15]
	s_mov_b32 m0, s40
	ds_read_b128 v[196:199], v190 offset:49152
	ds_read_b128 v[202:205], v190 offset:50176
	ds_read_b128 v[206:209], v190 offset:51200
	ds_read_b128 v[210:213], v190 offset:52224
	ds_read_b128 v[214:217], v190 offset:53248
	ds_read_b128 v[218:221], v190 offset:54272
	ds_read_b128 v[222:225], v190 offset:55296
	ds_read_b128 v[226:229], v190 offset:56320
	global_load_lds_dwordx4 v[180:181], off
	s_add_i32 m0, s40, 0x2000
	s_add_u32 s38, s38, 0x40080
	v_lshl_add_u64 v[180:181], v[230:231], 0, s[14:15]
	s_addc_u32 s39, s39, 0
	s_add_i32 s40, s66, s46
	global_load_lds_dwordx4 v[180:181], off
	v_lshl_add_u64 v[180:181], s[38:39], 0, v[130:131]
	s_mov_b32 m0, s40
	s_nop 0
	global_load_lds_dwordx4 v[180:181], off
	v_lshl_add_u64 v[180:181], s[38:39], 0, v[134:135]
	s_add_i32 m0, s40, 0x2000
	s_nop 0
	global_load_lds_dwordx4 v[180:181], off
	v_lshl_add_u64 v[180:181], v[232:233], 0, s[14:15]
	s_mov_b32 m0, s53
	s_nop 0
	global_load_lds_dwordx4 v[180:181], off
	v_lshl_add_u64 v[180:181], v[234:235], 0, s[14:15]
	s_mov_b32 m0, s54
	s_nop 0
	global_load_lds_dwordx4 v[180:181], off
	s_add_i32 s64, s64, 2
	s_add_u32 s36, s36, 0x100
	s_addc_u32 s37, s37, 0
	s_add_u32 s35, s35, 0x100
	s_addc_u32 s63, s63, 0
	s_cmp_gt_u32 s64, 13
	s_waitcnt vmcnt(8)
	s_waitcnt lgkmcnt(0)
	s_barrier
	s_setprio 1
	s_waitcnt lgkmcnt(0)
	v_mfma_f32_16x16x32_bf16 v[60:63], v[148:151], v[196:199], v[60:63]
	v_mfma_f32_16x16x32_bf16 v[56:59], v[156:159], v[196:199], v[56:59]
	v_mfma_f32_16x16x32_bf16 v[52:55], v[148:151], v[206:209], v[52:55]
	v_mfma_f32_16x16x32_bf16 v[44:47], v[156:159], v[206:209], v[44:47]
	v_mfma_f32_16x16x32_bf16 v[36:39], v[148:151], v[214:217], v[36:39]
	v_mfma_f32_16x16x32_bf16 v[28:31], v[156:159], v[214:217], v[28:31]
	v_mfma_f32_16x16x32_bf16 v[20:23], v[148:151], v[222:225], v[20:23]
	v_mfma_f32_16x16x32_bf16 v[12:15], v[156:159], v[222:225], v[12:15]
	v_mfma_f32_16x16x32_bf16 v[60:63], v[152:155], v[202:205], v[60:63]
	v_mfma_f32_16x16x32_bf16 v[56:59], v[160:163], v[202:205], v[56:59]
	v_mfma_f32_16x16x32_bf16 v[52:55], v[152:155], v[210:213], v[52:55]
	v_mfma_f32_16x16x32_bf16 v[44:47], v[160:163], v[210:213], v[44:47]
	v_mfma_f32_16x16x32_bf16 v[36:39], v[152:155], v[218:221], v[36:39]
	v_mfma_f32_16x16x32_bf16 v[28:31], v[160:163], v[218:221], v[28:31]
	v_mfma_f32_16x16x32_bf16 v[20:23], v[152:155], v[226:229], v[20:23]
	v_mfma_f32_16x16x32_bf16 v[12:15], v[160:163], v[226:229], v[12:15]
	s_setprio 0
	s_setprio 1
	v_mfma_f32_16x16x32_bf16 v[48:51], v[164:167], v[196:199], v[48:51]
	v_mfma_f32_16x16x32_bf16 v[40:43], v[172:175], v[196:199], v[40:43]
	v_mfma_f32_16x16x32_bf16 v[32:35], v[164:167], v[206:209], v[32:35]
	v_mfma_f32_16x16x32_bf16 v[24:27], v[172:175], v[206:209], v[24:27]
	v_mfma_f32_16x16x32_bf16 v[16:19], v[164:167], v[214:217], v[16:19]
	v_mfma_f32_16x16x32_bf16 v[8:11], v[172:175], v[214:217], v[8:11]
	v_mfma_f32_16x16x32_bf16 v[4:7], v[164:167], v[222:225], v[4:7]
	v_mfma_f32_16x16x32_bf16 v[0:3], v[172:175], v[222:225], v[0:3]
	v_mfma_f32_16x16x32_bf16 v[48:51], v[168:171], v[202:205], v[48:51]
	v_mfma_f32_16x16x32_bf16 v[40:43], v[176:179], v[202:205], v[40:43]
	v_mfma_f32_16x16x32_bf16 v[32:35], v[168:171], v[210:213], v[32:35]
	v_mfma_f32_16x16x32_bf16 v[24:27], v[176:179], v[210:213], v[24:27]
	v_mfma_f32_16x16x32_bf16 v[16:19], v[168:171], v[218:221], v[16:19]
	v_mfma_f32_16x16x32_bf16 v[8:11], v[176:179], v[218:221], v[8:11]
	v_mfma_f32_16x16x32_bf16 v[4:7], v[168:171], v[226:229], v[4:7]
	v_mfma_f32_16x16x32_bf16 v[0:3], v[176:179], v[226:229], v[0:3]
	s_setprio 0
	s_barrier
	s_cbranch_scc0 .LBB0_219
	s_and_b64 vcc, exec, s[16:17]
	s_cbranch_vccz .LBB0_222
	s_barrier

.LBB0_417:
	v_add_u32_e32 v140, s55, v196
	v_add_u32_e32 v199, s56, v196
	ds_read_b128 v[128:131], v140
	ds_read_b128 v[132:135], v140 offset:1024
	ds_read_b128 v[136:139], v140 offset:2048
	ds_read_b128 v[140:143], v140 offset:3072
	ds_read_b128 v[192:195], v199
	ds_read_b128 v[202:205], v199 offset:1024
	ds_read_b128 v[206:209], v199 offset:2048
	ds_read_b128 v[210:213], v199 offset:3072
	s_add_u32 s28, s24, 0xfffc0080
	s_addc_u32 s29, s25, -1
	s_cmp_eq_u32 s60, 12
	s_cselect_b32 s31, s15, s29
	s_cselect_b32 s30, s34, s28
	s_cselect_b32 s29, s13, s59
	s_cselect_b32 s28, s35, s58
	v_lshl_add_u64 v[246:247], s[24:25], 0, v[184:185]
	s_add_i32 m0, s43, 0xc000
	ds_read_b128 v[214:217], v198
	ds_read_b128 v[218:221], v198 offset:1024
	ds_read_b128 v[222:225], v198 offset:2048
	ds_read_b128 v[226:229], v198 offset:3072
	ds_read_b128 v[230:233], v198 offset:4096
	ds_read_b128 v[234:237], v198 offset:5120
	ds_read_b128 v[238:241], v198 offset:6144
	ds_read_b128 v[242:245], v198 offset:7168
	global_load_lds_dwordx4 v[246:247], off
	v_lshl_add_u64 v[246:247], s[24:25], 0, v[186:187]
	s_add_i32 m0, s43, 0xe000
	s_nop 0
	global_load_lds_dwordx4 v[246:247], off
	s_waitcnt vmcnt(8)
	s_waitcnt lgkmcnt(0)
	s_barrier
	s_setprio 1
	s_waitcnt lgkmcnt(0)
	v_mfma_f32_16x16x32_bf16 v[124:127], v[128:131], v[214:217], v[124:127]
	v_mfma_f32_16x16x32_bf16 v[120:123], v[136:139], v[214:217], v[120:123]
	v_mfma_f32_16x16x32_bf16 v[116:119], v[128:131], v[222:225], v[116:119]
	v_mfma_f32_16x16x32_bf16 v[112:115], v[136:139], v[222:225], v[112:115]
	v_mfma_f32_16x16x32_bf16 v[92:95], v[128:131], v[230:233], v[92:95]
	v_mfma_f32_16x16x32_bf16 v[88:91], v[136:139], v[230:233], v[88:91]
	v_mfma_f32_16x16x32_bf16 v[84:87], v[128:131], v[238:241], v[84:87]
	v_mfma_f32_16x16x32_bf16 v[80:83], v[136:139], v[238:241], v[80:83]
	v_mfma_f32_16x16x32_bf16 v[124:127], v[132:135], v[218:221], v[124:127]
	v_mfma_f32_16x16x32_bf16 v[120:123], v[140:143], v[218:221], v[120:123]
	v_mfma_f32_16x16x32_bf16 v[116:119], v[132:135], v[226:229], v[116:119]
	v_mfma_f32_16x16x32_bf16 v[112:115], v[140:143], v[226:229], v[112:115]
	v_mfma_f32_16x16x32_bf16 v[92:95], v[132:135], v[234:237], v[92:95]
	v_mfma_f32_16x16x32_bf16 v[88:91], v[140:143], v[234:237], v[88:91]
	v_mfma_f32_16x16x32_bf16 v[84:87], v[132:135], v[242:245], v[84:87]
	v_mfma_f32_16x16x32_bf16 v[80:83], v[140:143], v[242:245], v[80:83]
	s_setprio 0
	s_setprio 1
	v_mfma_f32_16x16x32_bf16 v[108:111], v[192:195], v[214:217], v[108:111]
	v_mfma_f32_16x16x32_bf16 v[104:107], v[206:209], v[214:217], v[104:107]
	v_mfma_f32_16x16x32_bf16 v[100:103], v[192:195], v[222:225], v[100:103]
	v_mfma_f32_16x16x32_bf16 v[96:99], v[206:209], v[222:225], v[96:99]
	v_mfma_f32_16x16x32_bf16 v[76:79], v[192:195], v[230:233], v[76:79]
	v_mfma_f32_16x16x32_bf16 v[72:75], v[206:209], v[230:233], v[72:75]
	v_mfma_f32_16x16x32_bf16 v[68:71], v[192:195], v[238:241], v[68:71]
	v_mfma_f32_16x16x32_bf16 v[64:67], v[206:209], v[238:241], v[64:67]
	v_mfma_f32_16x16x32_bf16 v[108:111], v[202:205], v[218:221], v[108:111]
	v_mfma_f32_16x16x32_bf16 v[104:107], v[210:213], v[218:221], v[104:107]
	v_mfma_f32_16x16x32_bf16 v[100:103], v[202:205], v[226:229], v[100:103]
	v_mfma_f32_16x16x32_bf16 v[96:99], v[210:213], v[226:229], v[96:99]
	v_mfma_f32_16x16x32_bf16 v[76:79], v[202:205], v[234:237], v[76:79]
	v_mfma_f32_16x16x32_bf16 v[72:75], v[210:213], v[234:237], v[72:75]
	v_mfma_f32_16x16x32_bf16 v[68:71], v[202:205], v[242:245], v[68:71]
	v_mfma_f32_16x16x32_bf16 v[64:67], v[210:213], v[242:245], v[64:67]
	s_setprio 0
	s_barrier
	s_add_i32 s61, s55, s40
	v_lshl_add_u64 v[246:247], s[28:29], 0, v[148:149]
	s_mov_b32 m0, s61
	ds_read_b128 v[214:217], v198 offset:16384
	ds_read_b128 v[218:221], v198 offset:17408
	ds_read_b128 v[222:225], v198 offset:18432
	ds_read_b128 v[226:229], v198 offset:19456
	ds_read_b128 v[230:233], v198 offset:20480
	ds_read_b128 v[234:237], v198 offset:21504
	ds_read_b128 v[238:241], v198 offset:22528
	ds_read_b128 v[242:245], v198 offset:23552
	global_load_lds_dwordx4 v[246:247], off
	s_add_i32 m0, s61, 0x2000
	s_add_u32 s62, s28, 0x40000
	v_lshl_add_u64 v[248:249], s[28:29], 0, v[144:145]
	s_addc_u32 s63, s29, 0
	s_add_i32 s61, s56, s40
	global_load_lds_dwordx4 v[248:249], off
	v_lshl_add_u64 v[250:251], s[62:63], 0, v[148:149]
	s_mov_b32 m0, s61
	v_lshl_add_u64 v[252:253], s[30:31], 0, v[146:147]
	global_load_lds_dwordx4 v[250:251], off
	v_lshl_add_u64 v[250:251], s[62:63], 0, v[144:145]
	s_add_i32 m0, s61, 0x2000
	s_nop 0
	global_load_lds_dwordx4 v[250:251], off
	v_lshl_add_u64 v[250:251], s[30:31], 0, v[150:151]
	s_mov_b32 m0, s43
	s_nop 0
	global_load_lds_dwordx4 v[250:251], off
	s_mov_b32 m0, s44
	s_nop 0
	global_load_lds_dwordx4 v[252:253], off
	s_waitcnt vmcnt(8)
	s_waitcnt lgkmcnt(0)
	s_barrier
	s_setprio 1
	s_waitcnt lgkmcnt(0)
	v_mfma_f32_16x16x32_bf16 v[60:63], v[128:131], v[214:217], v[60:63]
	v_mfma_f32_16x16x32_bf16 v[56:59], v[136:139], v[214:217], v[56:59]
	v_mfma_f32_16x16x32_bf16 v[52:55], v[128:131], v[222:225], v[52:55]
	v_mfma_f32_16x16x32_bf16 v[48:51], v[136:139], v[222:225], v[48:51]
	v_mfma_f32_16x16x32_bf16 v[28:31], v[128:131], v[230:233], v[28:31]
	v_mfma_f32_16x16x32_bf16 v[24:27], v[136:139], v[230:233], v[24:27]
	v_mfma_f32_16x16x32_bf16 v[20:23], v[128:131], v[238:241], v[20:23]
	v_mfma_f32_16x16x32_bf16 v[16:19], v[136:139], v[238:241], v[16:19]
	v_mfma_f32_16x16x32_bf16 v[60:63], v[132:135], v[218:221], v[60:63]
	v_mfma_f32_16x16x32_bf16 v[56:59], v[140:143], v[218:221], v[56:59]
	v_mfma_f32_16x16x32_bf16 v[52:55], v[132:135], v[226:229], v[52:55]
	v_mfma_f32_16x16x32_bf16 v[48:51], v[140:143], v[226:229], v[48:51]
	v_mfma_f32_16x16x32_bf16 v[28:31], v[132:135], v[234:237], v[28:31]
	v_mfma_f32_16x16x32_bf16 v[24:27], v[140:143], v[234:237], v[24:27]
	v_mfma_f32_16x16x32_bf16 v[20:23], v[132:135], v[242:245], v[20:23]
	v_mfma_f32_16x16x32_bf16 v[16:19], v[140:143], v[242:245], v[16:19]
	s_setprio 0
	s_setprio 1
	v_mfma_f32_16x16x32_bf16 v[44:47], v[192:195], v[214:217], v[44:47]
	v_mfma_f32_16x16x32_bf16 v[40:43], v[206:209], v[214:217], v[40:43]
	v_mfma_f32_16x16x32_bf16 v[36:39], v[192:195], v[222:225], v[36:39]
	v_mfma_f32_16x16x32_bf16 v[32:35], v[206:209], v[222:225], v[32:35]
	v_mfma_f32_16x16x32_bf16 v[12:15], v[192:195], v[230:233], v[12:15]
	v_mfma_f32_16x16x32_bf16 v[8:11], v[206:209], v[230:233], v[8:11]
	v_mfma_f32_16x16x32_bf16 v[4:7], v[192:195], v[238:241], v[4:7]
	v_mfma_f32_16x16x32_bf16 v[0:3], v[206:209], v[238:241], v[0:3]
	v_mfma_f32_16x16x32_bf16 v[44:47], v[202:205], v[218:221], v[44:47]
	v_mfma_f32_16x16x32_bf16 v[40:43], v[210:213], v[218:221], v[40:43]
	v_mfma_f32_16x16x32_bf16 v[36:39], v[202:205], v[226:229], v[36:39]
	v_mfma_f32_16x16x32_bf16 v[32:35], v[210:213], v[226:229], v[32:35]
	v_mfma_f32_16x16x32_bf16 v[12:15], v[202:205], v[234:237], v[12:15]
	v_mfma_f32_16x16x32_bf16 v[8:11], v[210:213], v[234:237], v[8:11]
	v_mfma_f32_16x16x32_bf16 v[4:7], v[202:205], v[242:245], v[4:7]
	v_mfma_f32_16x16x32_bf16 v[0:3], v[210:213], v[242:245], v[0:3]
	s_setprio 0
	s_barrier
	s_add_i32 s61, 0, 0x18000
	s_add_i32 s62, 0, 0x1c000
	v_add_u32_e32 v140, s61, v196
	v_add_u32_e32 v199, s62, v196
	ds_read_b128 v[128:131], v140
	ds_read_b128 v[132:135], v140 offset:1024
	ds_read_b128 v[136:139], v140 offset:2048
	ds_read_b128 v[140:143], v140 offset:3072
	ds_read_b128 v[192:195], v199
	ds_read_b128 v[202:205], v199 offset:1024
	ds_read_b128 v[206:209], v199 offset:2048
	ds_read_b128 v[210:213], v199 offset:3072
	s_add_u32 s30, s30, 0x40000
	s_addc_u32 s31, s31, 0
	s_mov_b32 m0, s45
	v_lshl_add_u64 v[200:201], s[30:31], 0, v[150:151]
	ds_read_b128 v[214:217], v198 offset:32768
	ds_read_b128 v[218:221], v198 offset:33792
	ds_read_b128 v[222:225], v198 offset:34816
	ds_read_b128 v[226:229], v198 offset:35840
	ds_read_b128 v[230:233], v198 offset:36864
	ds_read_b128 v[234:237], v198 offset:37888
	ds_read_b128 v[238:241], v198 offset:38912
	ds_read_b128 v[242:245], v198 offset:39936
	global_load_lds_dwordx4 v[200:201], off
	v_lshl_add_u64 v[200:201], s[30:31], 0, v[146:147]
	s_mov_b32 m0, s46
	s_nop 0
	global_load_lds_dwordx4 v[200:201], off
	s_waitcnt vmcnt(8)
	s_waitcnt lgkmcnt(0)
	s_barrier
	s_setprio 1
	s_waitcnt lgkmcnt(0)
	v_mfma_f32_16x16x32_bf16 v[124:127], v[128:131], v[214:217], v[124:127]
	v_mfma_f32_16x16x32_bf16 v[120:123], v[136:139], v[214:217], v[120:123]
	v_mfma_f32_16x16x32_bf16 v[116:119], v[128:131], v[222:225], v[116:119]
	v_mfma_f32_16x16x32_bf16 v[112:115], v[136:139], v[222:225], v[112:115]
	v_mfma_f32_16x16x32_bf16 v[92:95], v[128:131], v[230:233], v[92:95]
	v_mfma_f32_16x16x32_bf16 v[88:91], v[136:139], v[230:233], v[88:91]
	v_mfma_f32_16x16x32_bf16 v[84:87], v[128:131], v[238:241], v[84:87]
	v_mfma_f32_16x16x32_bf16 v[80:83], v[136:139], v[238:241], v[80:83]
	v_mfma_f32_16x16x32_bf16 v[124:127], v[132:135], v[218:221], v[124:127]
	v_mfma_f32_16x16x32_bf16 v[120:123], v[140:143], v[218:221], v[120:123]
	v_mfma_f32_16x16x32_bf16 v[116:119], v[132:135], v[226:229], v[116:119]
	v_mfma_f32_16x16x32_bf16 v[112:115], v[140:143], v[226:229], v[112:115]
	v_mfma_f32_16x16x32_bf16 v[92:95], v[132:135], v[234:237], v[92:95]
	v_mfma_f32_16x16x32_bf16 v[88:91], v[140:143], v[234:237], v[88:91]
	v_mfma_f32_16x16x32_bf16 v[84:87], v[132:135], v[242:245], v[84:87]
	v_mfma_f32_16x16x32_bf16 v[80:83], v[140:143], v[242:245], v[80:83]
	s_setprio 0
	s_setprio 1
	v_mfma_f32_16x16x32_bf16 v[108:111], v[192:195], v[214:217], v[108:111]
	v_mfma_f32_16x16x32_bf16 v[104:107], v[206:209], v[214:217], v[104:107]
	v_mfma_f32_16x16x32_bf16 v[100:103], v[192:195], v[222:225], v[100:103]
	v_mfma_f32_16x16x32_bf16 v[96:99], v[206:209], v[222:225], v[96:99]
	v_mfma_f32_16x16x32_bf16 v[76:79], v[192:195], v[230:233], v[76:79]
	v_mfma_f32_16x16x32_bf16 v[72:75], v[206:209], v[230:233], v[72:75]
	v_mfma_f32_16x16x32_bf16 v[68:71], v[192:195], v[238:241], v[68:71]
	v_mfma_f32_16x16x32_bf16 v[64:67], v[206:209], v[238:241], v[64:67]
	v_mfma_f32_16x16x32_bf16 v[108:111], v[202:205], v[218:221], v[108:111]
	v_mfma_f32_16x16x32_bf16 v[104:107], v[210:213], v[218:221], v[104:107]
	v_mfma_f32_16x16x32_bf16 v[100:103], v[202:205], v[226:229], v[100:103]
	v_mfma_f32_16x16x32_bf16 v[96:99], v[210:213], v[226:229], v[96:99]
	v_mfma_f32_16x16x32_bf16 v[76:79], v[202:205], v[234:237], v[76:79]
	v_mfma_f32_16x16x32_bf16 v[72:75], v[210:213], v[234:237], v[72:75]
	v_mfma_f32_16x16x32_bf16 v[68:71], v[202:205], v[242:245], v[68:71]
	v_mfma_f32_16x16x32_bf16 v[64:67], v[210:213], v[242:245], v[64:67]
	s_setprio 0
	s_barrier
	s_add_i32 s30, s61, s40
	v_lshl_add_u64 v[200:201], v[246:247], 0, s[8:9]
	s_mov_b32 m0, s30
	ds_read_b128 v[214:217], v198 offset:49152
	ds_read_b128 v[218:221], v198 offset:50176
	ds_read_b128 v[222:225], v198 offset:51200
	ds_read_b128 v[226:229], v198 offset:52224
	ds_read_b128 v[230:233], v198 offset:53248
	ds_read_b128 v[234:237], v198 offset:54272
	ds_read_b128 v[238:241], v198 offset:55296
	ds_read_b128 v[242:245], v198 offset:56320
	global_load_lds_dwordx4 v[200:201], off
	s_add_i32 m0, s30, 0x2000
	s_add_u32 s28, s28, 0x40080
	v_lshl_add_u64 v[200:201], v[248:249], 0, s[8:9]
	s_addc_u32 s29, s29, 0
	s_add_i32 s30, s62, s40
	global_load_lds_dwordx4 v[200:201], off
	v_lshl_add_u64 v[200:201], s[28:29], 0, v[148:149]
	s_mov_b32 m0, s30
	s_nop 0
	global_load_lds_dwordx4 v[200:201], off
	v_lshl_add_u64 v[200:201], s[28:29], 0, v[144:145]
	s_add_i32 m0, s30, 0x2000
	s_nop 0
	global_load_lds_dwordx4 v[200:201], off
	v_lshl_add_u64 v[200:201], v[250:251], 0, s[8:9]
	s_mov_b32 m0, s51
	s_nop 0
	global_load_lds_dwordx4 v[200:201], off
	v_lshl_add_u64 v[200:201], v[252:253], 0, s[8:9]
	s_mov_b32 m0, s52
	s_nop 0
	global_load_lds_dwordx4 v[200:201], off
	s_add_i32 s60, s60, 2
	s_add_u32 s24, s24, 0x100
	s_addc_u32 s25, s25, 0
	s_add_u32 s58, s58, 0x100
	s_addc_u32 s59, s59, 0
	s_cmp_gt_u32 s60, 13
	s_waitcnt vmcnt(8)
	s_waitcnt lgkmcnt(0)
	s_barrier
	s_setprio 1
	s_waitcnt lgkmcnt(0)
	v_mfma_f32_16x16x32_bf16 v[60:63], v[128:131], v[214:217], v[60:63]
	v_mfma_f32_16x16x32_bf16 v[56:59], v[136:139], v[214:217], v[56:59]
	v_mfma_f32_16x16x32_bf16 v[52:55], v[128:131], v[222:225], v[52:55]
	v_mfma_f32_16x16x32_bf16 v[48:51], v[136:139], v[222:225], v[48:51]
	v_mfma_f32_16x16x32_bf16 v[28:31], v[128:131], v[230:233], v[28:31]
	v_mfma_f32_16x16x32_bf16 v[24:27], v[136:139], v[230:233], v[24:27]
	v_mfma_f32_16x16x32_bf16 v[20:23], v[128:131], v[238:241], v[20:23]
	v_mfma_f32_16x16x32_bf16 v[16:19], v[136:139], v[238:241], v[16:19]
	v_mfma_f32_16x16x32_bf16 v[60:63], v[132:135], v[218:221], v[60:63]
	v_mfma_f32_16x16x32_bf16 v[56:59], v[140:143], v[218:221], v[56:59]
	v_mfma_f32_16x16x32_bf16 v[52:55], v[132:135], v[226:229], v[52:55]
	v_mfma_f32_16x16x32_bf16 v[48:51], v[140:143], v[226:229], v[48:51]
	v_mfma_f32_16x16x32_bf16 v[28:31], v[132:135], v[234:237], v[28:31]
	v_mfma_f32_16x16x32_bf16 v[24:27], v[140:143], v[234:237], v[24:27]
	v_mfma_f32_16x16x32_bf16 v[20:23], v[132:135], v[242:245], v[20:23]
	v_mfma_f32_16x16x32_bf16 v[16:19], v[140:143], v[242:245], v[16:19]
	s_setprio 0
	s_setprio 1
	v_mfma_f32_16x16x32_bf16 v[44:47], v[192:195], v[214:217], v[44:47]
	v_mfma_f32_16x16x32_bf16 v[40:43], v[206:209], v[214:217], v[40:43]
	v_mfma_f32_16x16x32_bf16 v[36:39], v[192:195], v[222:225], v[36:39]
	v_mfma_f32_16x16x32_bf16 v[32:35], v[206:209], v[222:225], v[32:35]
	v_mfma_f32_16x16x32_bf16 v[12:15], v[192:195], v[230:233], v[12:15]
	v_mfma_f32_16x16x32_bf16 v[8:11], v[206:209], v[230:233], v[8:11]
	v_mfma_f32_16x16x32_bf16 v[4:7], v[192:195], v[238:241], v[4:7]
	v_mfma_f32_16x16x32_bf16 v[0:3], v[206:209], v[238:241], v[0:3]
	v_mfma_f32_16x16x32_bf16 v[44:47], v[202:205], v[218:221], v[44:47]
	v_mfma_f32_16x16x32_bf16 v[40:43], v[210:213], v[218:221], v[40:43]
	v_mfma_f32_16x16x32_bf16 v[36:39], v[202:205], v[226:229], v[36:39]
	v_mfma_f32_16x16x32_bf16 v[32:35], v[210:213], v[226:229], v[32:35]
	v_mfma_f32_16x16x32_bf16 v[12:15], v[202:205], v[234:237], v[12:15]
	v_mfma_f32_16x16x32_bf16 v[8:11], v[210:213], v[234:237], v[8:11]
	v_mfma_f32_16x16x32_bf16 v[4:7], v[202:205], v[242:245], v[4:7]
	v_mfma_f32_16x16x32_bf16 v[0:3], v[210:213], v[242:245], v[0:3]
	s_setprio 0
	s_barrier
	s_cbranch_scc0 .LBB0_417
	s_and_b64 vcc, exec, s[10:11]
	s_cbranch_vccz .LBB0_420
	s_barrier

.LBB0_573:
	ds_read_b128 v[150:153], v147
	ds_read_b128 v[154:157], v147 offset:1024
	ds_read_b128 v[158:161], v147 offset:2048
	ds_read_b128 v[162:165], v147 offset:3072
	ds_read_b128 v[166:169], v148
	ds_read_b128 v[170:173], v148 offset:1024
	ds_read_b128 v[174:177], v148 offset:2048
	ds_read_b128 v[178:181], v148 offset:3072
	s_add_u32 s30, s28, 0xfffc0080
	s_addc_u32 s31, s29, -1
	s_cmp_eq_u32 s58, 12
	s_cselect_b32 s35, s15, s31
	s_cselect_b32 s34, s54, s30
	s_cselect_b32 s31, s13, s57
	s_cselect_b32 s30, s55, s56
	v_lshl_add_u64 v[198:199], s[28:29], 0, v[136:137]
	s_add_i32 m0, s25, 0xc000
	ds_read_b128 v[182:185], v149
	ds_read_b128 v[186:189], v149 offset:1024
	ds_read_b128 v[190:193], v149 offset:2048
	ds_read_b128 v[194:197], v149 offset:3072
	ds_read_b128 v[202:205], v149 offset:4096
	ds_read_b128 v[206:209], v149 offset:5120
	ds_read_b128 v[210:213], v149 offset:6144
	ds_read_b128 v[214:217], v149 offset:7168
	global_load_lds_dwordx4 v[198:199], off
	v_lshl_add_u64 v[198:199], s[28:29], 0, v[138:139]
	s_add_i32 m0, s25, 0xe000
	s_nop 0
	global_load_lds_dwordx4 v[198:199], off
	s_waitcnt vmcnt(8)
	s_waitcnt lgkmcnt(0)
	s_barrier
	s_setprio 1
	s_waitcnt lgkmcnt(0)
	v_mfma_f32_16x16x32_bf16 v[124:127], v[150:153], v[182:185], v[124:127]
	v_mfma_f32_16x16x32_bf16 v[116:119], v[158:161], v[182:185], v[116:119]
	v_mfma_f32_16x16x32_bf16 v[108:111], v[150:153], v[190:193], v[108:111]
	v_mfma_f32_16x16x32_bf16 v[100:103], v[158:161], v[190:193], v[100:103]
	v_mfma_f32_16x16x32_bf16 v[92:95], v[150:153], v[202:205], v[92:95]
	v_mfma_f32_16x16x32_bf16 v[84:87], v[158:161], v[202:205], v[84:87]
	v_mfma_f32_16x16x32_bf16 v[76:79], v[150:153], v[210:213], v[76:79]
	v_mfma_f32_16x16x32_bf16 v[68:71], v[158:161], v[210:213], v[68:71]
	v_mfma_f32_16x16x32_bf16 v[124:127], v[154:157], v[186:189], v[124:127]
	v_mfma_f32_16x16x32_bf16 v[116:119], v[162:165], v[186:189], v[116:119]
	v_mfma_f32_16x16x32_bf16 v[108:111], v[154:157], v[194:197], v[108:111]
	v_mfma_f32_16x16x32_bf16 v[100:103], v[162:165], v[194:197], v[100:103]
	v_mfma_f32_16x16x32_bf16 v[92:95], v[154:157], v[206:209], v[92:95]
	v_mfma_f32_16x16x32_bf16 v[84:87], v[162:165], v[206:209], v[84:87]
	v_mfma_f32_16x16x32_bf16 v[76:79], v[154:157], v[214:217], v[76:79]
	v_mfma_f32_16x16x32_bf16 v[68:71], v[162:165], v[214:217], v[68:71]
	s_setprio 0
	s_setprio 1
	v_mfma_f32_16x16x32_bf16 v[120:123], v[166:169], v[182:185], v[120:123]
	v_mfma_f32_16x16x32_bf16 v[112:115], v[174:177], v[182:185], v[112:115]
	v_mfma_f32_16x16x32_bf16 v[104:107], v[166:169], v[190:193], v[104:107]
	v_mfma_f32_16x16x32_bf16 v[96:99], v[174:177], v[190:193], v[96:99]
	v_mfma_f32_16x16x32_bf16 v[88:91], v[166:169], v[202:205], v[88:91]
	v_mfma_f32_16x16x32_bf16 v[80:83], v[174:177], v[202:205], v[80:83]
	v_mfma_f32_16x16x32_bf16 v[72:75], v[166:169], v[210:213], v[72:75]
	v_mfma_f32_16x16x32_bf16 v[64:67], v[174:177], v[210:213], v[64:67]
	v_mfma_f32_16x16x32_bf16 v[120:123], v[170:173], v[186:189], v[120:123]
	v_mfma_f32_16x16x32_bf16 v[112:115], v[178:181], v[186:189], v[112:115]
	v_mfma_f32_16x16x32_bf16 v[104:107], v[170:173], v[194:197], v[104:107]
	v_mfma_f32_16x16x32_bf16 v[96:99], v[178:181], v[194:197], v[96:99]
	v_mfma_f32_16x16x32_bf16 v[88:91], v[170:173], v[206:209], v[88:91]
	v_mfma_f32_16x16x32_bf16 v[80:83], v[178:181], v[206:209], v[80:83]
	v_mfma_f32_16x16x32_bf16 v[72:75], v[170:173], v[214:217], v[72:75]
	v_mfma_f32_16x16x32_bf16 v[64:67], v[178:181], v[214:217], v[64:67]
	s_setprio 0
	s_barrier
	s_add_i32 s59, s51, s40
	v_lshl_add_u64 v[198:199], s[30:31], 0, v[132:133]
	s_mov_b32 m0, s59
	ds_read_b128 v[182:185], v149 offset:16384
	ds_read_b128 v[186:189], v149 offset:17408
	ds_read_b128 v[190:193], v149 offset:18432
	ds_read_b128 v[194:197], v149 offset:19456
	ds_read_b128 v[202:205], v149 offset:20480
	ds_read_b128 v[206:209], v149 offset:21504
	ds_read_b128 v[210:213], v149 offset:22528
	ds_read_b128 v[214:217], v149 offset:23552
	global_load_lds_dwordx4 v[198:199], off
	s_add_i32 m0, s59, 0x2000
	s_add_u32 s60, s30, 0x40000
	v_lshl_add_u64 v[200:201], s[30:31], 0, v[128:129]
	s_addc_u32 s61, s31, 0
	s_add_i32 s59, s52, s40
	global_load_lds_dwordx4 v[200:201], off
	v_lshl_add_u64 v[218:219], s[60:61], 0, v[132:133]
	s_mov_b32 m0, s59
	v_lshl_add_u64 v[220:221], s[34:35], 0, v[130:131]
	global_load_lds_dwordx4 v[218:219], off
	v_lshl_add_u64 v[218:219], s[60:61], 0, v[128:129]
	s_add_i32 m0, s59, 0x2000
	s_nop 0
	global_load_lds_dwordx4 v[218:219], off
	v_lshl_add_u64 v[218:219], s[34:35], 0, v[134:135]
	s_mov_b32 m0, s25
	s_nop 0
	global_load_lds_dwordx4 v[218:219], off
	s_mov_b32 m0, s43
	s_nop 0
	global_load_lds_dwordx4 v[220:221], off
	s_waitcnt vmcnt(8)
	s_waitcnt lgkmcnt(0)
	s_barrier
	s_setprio 1
	s_waitcnt lgkmcnt(0)
	v_mfma_f32_16x16x32_bf16 v[60:63], v[150:153], v[182:185], v[60:63]
	v_mfma_f32_16x16x32_bf16 v[52:55], v[158:161], v[182:185], v[52:55]
	v_mfma_f32_16x16x32_bf16 v[44:47], v[150:153], v[190:193], v[44:47]
	v_mfma_f32_16x16x32_bf16 v[36:39], v[158:161], v[190:193], v[36:39]
	v_mfma_f32_16x16x32_bf16 v[28:31], v[150:153], v[202:205], v[28:31]
	v_mfma_f32_16x16x32_bf16 v[20:23], v[158:161], v[202:205], v[20:23]
	v_mfma_f32_16x16x32_bf16 v[12:15], v[150:153], v[210:213], v[12:15]
	v_mfma_f32_16x16x32_bf16 v[4:7], v[158:161], v[210:213], v[4:7]
	v_mfma_f32_16x16x32_bf16 v[60:63], v[154:157], v[186:189], v[60:63]
	v_mfma_f32_16x16x32_bf16 v[52:55], v[162:165], v[186:189], v[52:55]
	v_mfma_f32_16x16x32_bf16 v[44:47], v[154:157], v[194:197], v[44:47]
	v_mfma_f32_16x16x32_bf16 v[36:39], v[162:165], v[194:197], v[36:39]
	v_mfma_f32_16x16x32_bf16 v[28:31], v[154:157], v[206:209], v[28:31]
	v_mfma_f32_16x16x32_bf16 v[20:23], v[162:165], v[206:209], v[20:23]
	v_mfma_f32_16x16x32_bf16 v[12:15], v[154:157], v[214:217], v[12:15]
	v_mfma_f32_16x16x32_bf16 v[4:7], v[162:165], v[214:217], v[4:7]
	s_setprio 0
	s_setprio 1
	v_mfma_f32_16x16x32_bf16 v[56:59], v[166:169], v[182:185], v[56:59]
	v_mfma_f32_16x16x32_bf16 v[48:51], v[174:177], v[182:185], v[48:51]
	v_mfma_f32_16x16x32_bf16 v[40:43], v[166:169], v[190:193], v[40:43]
	v_mfma_f32_16x16x32_bf16 v[32:35], v[174:177], v[190:193], v[32:35]
	v_mfma_f32_16x16x32_bf16 v[24:27], v[166:169], v[202:205], v[24:27]
	v_mfma_f32_16x16x32_bf16 v[16:19], v[174:177], v[202:205], v[16:19]
	v_mfma_f32_16x16x32_bf16 v[8:11], v[166:169], v[210:213], v[8:11]
	v_mfma_f32_16x16x32_bf16 v[0:3], v[174:177], v[210:213], v[0:3]
	v_mfma_f32_16x16x32_bf16 v[56:59], v[170:173], v[186:189], v[56:59]
	v_mfma_f32_16x16x32_bf16 v[48:51], v[178:181], v[186:189], v[48:51]
	v_mfma_f32_16x16x32_bf16 v[40:43], v[170:173], v[194:197], v[40:43]
	v_mfma_f32_16x16x32_bf16 v[32:35], v[178:181], v[194:197], v[32:35]
	v_mfma_f32_16x16x32_bf16 v[24:27], v[170:173], v[206:209], v[24:27]
	v_mfma_f32_16x16x32_bf16 v[16:19], v[178:181], v[206:209], v[16:19]
	v_mfma_f32_16x16x32_bf16 v[8:11], v[170:173], v[214:217], v[8:11]
	v_mfma_f32_16x16x32_bf16 v[0:3], v[178:181], v[214:217], v[0:3]
	s_setprio 0
	s_barrier
	s_add_i32 s59, 0, 0x18000
	s_add_i32 s60, 0, 0x1c000
	v_add_u32_e32 v162, s59, v145
	v_add_u32_e32 v178, s60, v145
	ds_read_b128 v[150:153], v162
	ds_read_b128 v[154:157], v162 offset:1024
	ds_read_b128 v[158:161], v162 offset:2048
	ds_read_b128 v[162:165], v162 offset:3072
	ds_read_b128 v[166:169], v178
	ds_read_b128 v[170:173], v178 offset:1024
	ds_read_b128 v[174:177], v178 offset:2048
	ds_read_b128 v[178:181], v178 offset:3072
	s_add_u32 s34, s34, 0x40000
	s_addc_u32 s35, s35, 0
	s_mov_b32 m0, s44
	v_lshl_add_u64 v[222:223], s[34:35], 0, v[134:135]
	ds_read_b128 v[182:185], v149 offset:32768
	ds_read_b128 v[186:189], v149 offset:33792
	ds_read_b128 v[190:193], v149 offset:34816
	ds_read_b128 v[194:197], v149 offset:35840
	ds_read_b128 v[202:205], v149 offset:36864
	ds_read_b128 v[206:209], v149 offset:37888
	ds_read_b128 v[210:213], v149 offset:38912
	ds_read_b128 v[214:217], v149 offset:39936
	global_load_lds_dwordx4 v[222:223], off
	v_lshl_add_u64 v[222:223], s[34:35], 0, v[130:131]
	s_mov_b32 m0, s45
	s_nop 0
	global_load_lds_dwordx4 v[222:223], off
	s_waitcnt vmcnt(8)
	s_waitcnt lgkmcnt(0)
	s_barrier
	s_setprio 1
	s_waitcnt lgkmcnt(0)
	v_mfma_f32_16x16x32_bf16 v[124:127], v[150:153], v[182:185], v[124:127]
	v_mfma_f32_16x16x32_bf16 v[116:119], v[158:161], v[182:185], v[116:119]
	v_mfma_f32_16x16x32_bf16 v[108:111], v[150:153], v[190:193], v[108:111]
	v_mfma_f32_16x16x32_bf16 v[100:103], v[158:161], v[190:193], v[100:103]
	v_mfma_f32_16x16x32_bf16 v[92:95], v[150:153], v[202:205], v[92:95]
	v_mfma_f32_16x16x32_bf16 v[84:87], v[158:161], v[202:205], v[84:87]
	v_mfma_f32_16x16x32_bf16 v[76:79], v[150:153], v[210:213], v[76:79]
	v_mfma_f32_16x16x32_bf16 v[68:71], v[158:161], v[210:213], v[68:71]
	v_mfma_f32_16x16x32_bf16 v[124:127], v[154:157], v[186:189], v[124:127]
	v_mfma_f32_16x16x32_bf16 v[116:119], v[162:165], v[186:189], v[116:119]
	v_mfma_f32_16x16x32_bf16 v[108:111], v[154:157], v[194:197], v[108:111]
	v_mfma_f32_16x16x32_bf16 v[100:103], v[162:165], v[194:197], v[100:103]
	v_mfma_f32_16x16x32_bf16 v[92:95], v[154:157], v[206:209], v[92:95]
	v_mfma_f32_16x16x32_bf16 v[84:87], v[162:165], v[206:209], v[84:87]
	v_mfma_f32_16x16x32_bf16 v[76:79], v[154:157], v[214:217], v[76:79]
	v_mfma_f32_16x16x32_bf16 v[68:71], v[162:165], v[214:217], v[68:71]
	s_setprio 0
	s_setprio 1
	v_mfma_f32_16x16x32_bf16 v[120:123], v[166:169], v[182:185], v[120:123]
	v_mfma_f32_16x16x32_bf16 v[112:115], v[174:177], v[182:185], v[112:115]
	v_mfma_f32_16x16x32_bf16 v[104:107], v[166:169], v[190:193], v[104:107]
	v_mfma_f32_16x16x32_bf16 v[96:99], v[174:177], v[190:193], v[96:99]
	v_mfma_f32_16x16x32_bf16 v[88:91], v[166:169], v[202:205], v[88:91]
	v_mfma_f32_16x16x32_bf16 v[80:83], v[174:177], v[202:205], v[80:83]
	v_mfma_f32_16x16x32_bf16 v[72:75], v[166:169], v[210:213], v[72:75]
	v_mfma_f32_16x16x32_bf16 v[64:67], v[174:177], v[210:213], v[64:67]
	v_mfma_f32_16x16x32_bf16 v[120:123], v[170:173], v[186:189], v[120:123]
	v_mfma_f32_16x16x32_bf16 v[112:115], v[178:181], v[186:189], v[112:115]
	v_mfma_f32_16x16x32_bf16 v[104:107], v[170:173], v[194:197], v[104:107]
	v_mfma_f32_16x16x32_bf16 v[96:99], v[178:181], v[194:197], v[96:99]
	v_mfma_f32_16x16x32_bf16 v[88:91], v[170:173], v[206:209], v[88:91]
	v_mfma_f32_16x16x32_bf16 v[80:83], v[178:181], v[206:209], v[80:83]
	v_mfma_f32_16x16x32_bf16 v[72:75], v[170:173], v[214:217], v[72:75]
	v_mfma_f32_16x16x32_bf16 v[64:67], v[178:181], v[214:217], v[64:67]
	s_setprio 0
	s_barrier
	s_add_i32 s34, s59, s40
	v_lshl_add_u64 v[198:199], v[198:199], 0, s[8:9]
	s_mov_b32 m0, s34
	ds_read_b128 v[182:185], v149 offset:49152
	ds_read_b128 v[186:189], v149 offset:50176
	ds_read_b128 v[190:193], v149 offset:51200
	ds_read_b128 v[194:197], v149 offset:52224
	ds_read_b128 v[202:205], v149 offset:53248
	ds_read_b128 v[206:209], v149 offset:54272
	ds_read_b128 v[210:213], v149 offset:55296
	ds_read_b128 v[214:217], v149 offset:56320
	global_load_lds_dwordx4 v[198:199], off
	s_add_i32 m0, s34, 0x2000
	s_add_u32 s30, s30, 0x40080
	v_lshl_add_u64 v[198:199], v[200:201], 0, s[8:9]
	s_addc_u32 s31, s31, 0
	s_add_i32 s34, s60, s40
	global_load_lds_dwordx4 v[198:199], off
	v_lshl_add_u64 v[198:199], s[30:31], 0, v[132:133]
	s_mov_b32 m0, s34
	s_nop 0
	global_load_lds_dwordx4 v[198:199], off
	v_lshl_add_u64 v[198:199], s[30:31], 0, v[128:129]
	s_add_i32 m0, s34, 0x2000
	s_nop 0
	global_load_lds_dwordx4 v[198:199], off
	v_lshl_add_u64 v[198:199], v[218:219], 0, s[8:9]
	s_mov_b32 m0, s47
	s_nop 0
	global_load_lds_dwordx4 v[198:199], off
	v_lshl_add_u64 v[198:199], v[220:221], 0, s[8:9]
	s_mov_b32 m0, s48
	s_nop 0
	global_load_lds_dwordx4 v[198:199], off
	s_add_i32 s58, s58, 2
	s_add_u32 s28, s28, 0x100
	s_addc_u32 s29, s29, 0
	s_add_u32 s56, s56, 0x100
	s_addc_u32 s57, s57, 0
	s_cmp_gt_u32 s58, 13
	s_waitcnt vmcnt(8)
	s_waitcnt lgkmcnt(0)
	s_barrier
	s_setprio 1
	s_waitcnt lgkmcnt(0)
	v_mfma_f32_16x16x32_bf16 v[60:63], v[150:153], v[182:185], v[60:63]
	v_mfma_f32_16x16x32_bf16 v[52:55], v[158:161], v[182:185], v[52:55]
	v_mfma_f32_16x16x32_bf16 v[44:47], v[150:153], v[190:193], v[44:47]
	v_mfma_f32_16x16x32_bf16 v[36:39], v[158:161], v[190:193], v[36:39]
	v_mfma_f32_16x16x32_bf16 v[28:31], v[150:153], v[202:205], v[28:31]
	v_mfma_f32_16x16x32_bf16 v[20:23], v[158:161], v[202:205], v[20:23]
	v_mfma_f32_16x16x32_bf16 v[12:15], v[150:153], v[210:213], v[12:15]
	v_mfma_f32_16x16x32_bf16 v[4:7], v[158:161], v[210:213], v[4:7]
	v_mfma_f32_16x16x32_bf16 v[60:63], v[154:157], v[186:189], v[60:63]
	v_mfma_f32_16x16x32_bf16 v[52:55], v[162:165], v[186:189], v[52:55]
	v_mfma_f32_16x16x32_bf16 v[44:47], v[154:157], v[194:197], v[44:47]
	v_mfma_f32_16x16x32_bf16 v[36:39], v[162:165], v[194:197], v[36:39]
	v_mfma_f32_16x16x32_bf16 v[28:31], v[154:157], v[206:209], v[28:31]
	v_mfma_f32_16x16x32_bf16 v[20:23], v[162:165], v[206:209], v[20:23]
	v_mfma_f32_16x16x32_bf16 v[12:15], v[154:157], v[214:217], v[12:15]
	v_mfma_f32_16x16x32_bf16 v[4:7], v[162:165], v[214:217], v[4:7]
	s_setprio 0
	s_setprio 1
	v_mfma_f32_16x16x32_bf16 v[56:59], v[166:169], v[182:185], v[56:59]
	v_mfma_f32_16x16x32_bf16 v[48:51], v[174:177], v[182:185], v[48:51]
	v_mfma_f32_16x16x32_bf16 v[40:43], v[166:169], v[190:193], v[40:43]
	v_mfma_f32_16x16x32_bf16 v[32:35], v[174:177], v[190:193], v[32:35]
	v_mfma_f32_16x16x32_bf16 v[24:27], v[166:169], v[202:205], v[24:27]
	v_mfma_f32_16x16x32_bf16 v[16:19], v[174:177], v[202:205], v[16:19]
	v_mfma_f32_16x16x32_bf16 v[8:11], v[166:169], v[210:213], v[8:11]
	v_mfma_f32_16x16x32_bf16 v[0:3], v[174:177], v[210:213], v[0:3]
	v_mfma_f32_16x16x32_bf16 v[56:59], v[170:173], v[186:189], v[56:59]
	v_mfma_f32_16x16x32_bf16 v[48:51], v[178:181], v[186:189], v[48:51]
	v_mfma_f32_16x16x32_bf16 v[40:43], v[170:173], v[194:197], v[40:43]
	v_mfma_f32_16x16x32_bf16 v[32:35], v[178:181], v[194:197], v[32:35]
	v_mfma_f32_16x16x32_bf16 v[24:27], v[170:173], v[206:209], v[24:27]
	v_mfma_f32_16x16x32_bf16 v[16:19], v[178:181], v[206:209], v[16:19]
	v_mfma_f32_16x16x32_bf16 v[8:11], v[170:173], v[214:217], v[8:11]
	v_mfma_f32_16x16x32_bf16 v[0:3], v[178:181], v[214:217], v[0:3]
	s_setprio 0
	s_barrier
	s_cbranch_scc0 .LBB0_573
	s_and_b64 vcc, exec, s[10:11]
	s_cbranch_vccz .LBB0_576
	s_barrier

.LBB0_648:
	ds_read_b128 v[128:131], v182
	ds_read_b128 v[132:135], v182 offset:1024
	ds_read_b128 v[136:139], v182 offset:2048
	ds_read_b128 v[140:143], v182 offset:3072
	ds_read_b128 v[176:179], v183
	ds_read_b128 v[186:189], v183 offset:1024
	ds_read_b128 v[190:193], v183 offset:2048
	ds_read_b128 v[194:197], v183 offset:3072
	s_add_u32 s16, s14, 0x100
	s_addc_u32 s17, s15, 0
	s_cmp_eq_u32 s57, 40
	s_cselect_b32 s25, s5, s17
	s_cselect_b32 s24, s4, s16
	s_cselect_b32 s19, s13, s56
	s_cselect_b32 s18, s12, s55
	v_lshl_add_u64 v[198:199], s[14:15], 0, v[168:169]
	s_add_i32 m0, s37, 0xc000
	ds_read_b128 v[202:205], v184
	ds_read_b128 v[206:209], v184 offset:1024
	ds_read_b128 v[210:213], v184 offset:2048
	ds_read_b128 v[214:217], v184 offset:3072
	ds_read_b128 v[218:221], v184 offset:4096
	ds_read_b128 v[222:225], v184 offset:5120
	ds_read_b128 v[226:229], v184 offset:6144
	ds_read_b128 v[230:233], v184 offset:7168
	global_load_lds_dwordx4 v[198:199], off
	v_lshl_add_u64 v[198:199], s[14:15], 0, v[170:171]
	s_add_i32 m0, s37, 0xe000
	s_nop 0
	global_load_lds_dwordx4 v[198:199], off
	s_waitcnt vmcnt(8)
	s_waitcnt lgkmcnt(0)
	s_barrier
	s_setprio 1
	s_waitcnt lgkmcnt(0)
	v_mfma_f32_16x16x32_bf16 v[124:127], v[128:131], v[202:205], v[124:127]
	v_mfma_f32_16x16x32_bf16 v[120:123], v[136:139], v[202:205], v[120:123]
	v_mfma_f32_16x16x32_bf16 v[116:119], v[128:131], v[210:213], v[116:119]
	v_mfma_f32_16x16x32_bf16 v[112:115], v[136:139], v[210:213], v[112:115]
	v_mfma_f32_16x16x32_bf16 v[92:95], v[128:131], v[218:221], v[92:95]
	v_mfma_f32_16x16x32_bf16 v[88:91], v[136:139], v[218:221], v[88:91]
	v_mfma_f32_16x16x32_bf16 v[76:79], v[128:131], v[226:229], v[76:79]
	v_mfma_f32_16x16x32_bf16 v[72:75], v[136:139], v[226:229], v[72:75]
	v_mfma_f32_16x16x32_bf16 v[124:127], v[132:135], v[206:209], v[124:127]
	v_mfma_f32_16x16x32_bf16 v[120:123], v[140:143], v[206:209], v[120:123]
	v_mfma_f32_16x16x32_bf16 v[116:119], v[132:135], v[214:217], v[116:119]
	v_mfma_f32_16x16x32_bf16 v[112:115], v[140:143], v[214:217], v[112:115]
	v_mfma_f32_16x16x32_bf16 v[92:95], v[132:135], v[222:225], v[92:95]
	v_mfma_f32_16x16x32_bf16 v[88:91], v[140:143], v[222:225], v[88:91]
	v_mfma_f32_16x16x32_bf16 v[76:79], v[132:135], v[230:233], v[76:79]
	v_mfma_f32_16x16x32_bf16 v[72:75], v[140:143], v[230:233], v[72:75]
	s_setprio 0
	s_setprio 1
	v_mfma_f32_16x16x32_bf16 v[108:111], v[176:179], v[202:205], v[108:111]
	v_mfma_f32_16x16x32_bf16 v[104:107], v[190:193], v[202:205], v[104:107]
	v_mfma_f32_16x16x32_bf16 v[100:103], v[176:179], v[210:213], v[100:103]
	v_mfma_f32_16x16x32_bf16 v[96:99], v[190:193], v[210:213], v[96:99]
	v_mfma_f32_16x16x32_bf16 v[84:87], v[176:179], v[218:221], v[84:87]
	v_mfma_f32_16x16x32_bf16 v[80:83], v[190:193], v[218:221], v[80:83]
	v_mfma_f32_16x16x32_bf16 v[68:71], v[176:179], v[226:229], v[68:71]
	v_mfma_f32_16x16x32_bf16 v[64:67], v[190:193], v[226:229], v[64:67]
	v_mfma_f32_16x16x32_bf16 v[108:111], v[186:189], v[206:209], v[108:111]
	v_mfma_f32_16x16x32_bf16 v[104:107], v[194:197], v[206:209], v[104:107]
	v_mfma_f32_16x16x32_bf16 v[100:103], v[186:189], v[214:217], v[100:103]
	v_mfma_f32_16x16x32_bf16 v[96:99], v[194:197], v[214:217], v[96:99]
	v_mfma_f32_16x16x32_bf16 v[84:87], v[186:189], v[222:225], v[84:87]
	v_mfma_f32_16x16x32_bf16 v[80:83], v[194:197], v[222:225], v[80:83]
	v_mfma_f32_16x16x32_bf16 v[68:71], v[186:189], v[230:233], v[68:71]
	v_mfma_f32_16x16x32_bf16 v[64:67], v[194:197], v[230:233], v[64:67]
	s_setprio 0
	s_barrier
	s_add_i32 s14, s50, s34
	v_lshl_add_u64 v[198:199], s[18:19], 0, v[148:149]
	s_mov_b32 m0, s14
	ds_read_b128 v[202:205], v184 offset:16384
	ds_read_b128 v[206:209], v184 offset:17408
	ds_read_b128 v[210:213], v184 offset:18432
	ds_read_b128 v[214:217], v184 offset:19456
	ds_read_b128 v[218:221], v184 offset:20480
	ds_read_b128 v[222:225], v184 offset:21504
	ds_read_b128 v[226:229], v184 offset:22528
	ds_read_b128 v[230:233], v184 offset:23552
	global_load_lds_dwordx4 v[198:199], off
	s_add_i32 m0, s14, 0x2000
	s_add_u32 s14, s18, 0xb0000
	v_lshl_add_u64 v[200:201], s[18:19], 0, v[144:145]
	s_addc_u32 s15, s19, 0
	s_add_i32 s58, s51, s34
	global_load_lds_dwordx4 v[200:201], off
	v_lshl_add_u64 v[234:235], s[14:15], 0, v[148:149]
	s_mov_b32 m0, s58
	v_lshl_add_u64 v[236:237], s[24:25], 0, v[146:147]
	global_load_lds_dwordx4 v[234:235], off
	v_lshl_add_u64 v[234:235], s[14:15], 0, v[144:145]
	s_add_i32 m0, s58, 0x2000
	s_nop 0
	global_load_lds_dwordx4 v[234:235], off
	v_lshl_add_u64 v[234:235], s[24:25], 0, v[150:151]
	s_mov_b32 m0, s37
	s_nop 0
	global_load_lds_dwordx4 v[234:235], off
	s_mov_b32 m0, s38
	s_nop 0
	global_load_lds_dwordx4 v[236:237], off
	s_waitcnt vmcnt(8)
	s_waitcnt lgkmcnt(0)
	s_barrier
	s_setprio 1
	s_waitcnt lgkmcnt(0)
	v_mfma_f32_16x16x32_bf16 v[60:63], v[128:131], v[202:205], v[60:63]
	v_mfma_f32_16x16x32_bf16 v[56:59], v[136:139], v[202:205], v[56:59]
	v_mfma_f32_16x16x32_bf16 v[44:47], v[128:131], v[210:213], v[44:47]
	v_mfma_f32_16x16x32_bf16 v[40:43], v[136:139], v[210:213], v[40:43]
	v_mfma_f32_16x16x32_bf16 v[28:31], v[128:131], v[218:221], v[28:31]
	v_mfma_f32_16x16x32_bf16 v[24:27], v[136:139], v[218:221], v[24:27]
	v_mfma_f32_16x16x32_bf16 v[12:15], v[128:131], v[226:229], v[12:15]
	v_mfma_f32_16x16x32_bf16 v[8:11], v[136:139], v[226:229], v[8:11]
	v_mfma_f32_16x16x32_bf16 v[60:63], v[132:135], v[206:209], v[60:63]
	v_mfma_f32_16x16x32_bf16 v[56:59], v[140:143], v[206:209], v[56:59]
	v_mfma_f32_16x16x32_bf16 v[44:47], v[132:135], v[214:217], v[44:47]
	v_mfma_f32_16x16x32_bf16 v[40:43], v[140:143], v[214:217], v[40:43]
	v_mfma_f32_16x16x32_bf16 v[28:31], v[132:135], v[222:225], v[28:31]
	v_mfma_f32_16x16x32_bf16 v[24:27], v[140:143], v[222:225], v[24:27]
	v_mfma_f32_16x16x32_bf16 v[12:15], v[132:135], v[230:233], v[12:15]
	v_mfma_f32_16x16x32_bf16 v[8:11], v[140:143], v[230:233], v[8:11]
	s_setprio 0
	s_setprio 1
	v_mfma_f32_16x16x32_bf16 v[52:55], v[176:179], v[202:205], v[52:55]
	v_mfma_f32_16x16x32_bf16 v[48:51], v[190:193], v[202:205], v[48:51]
	v_mfma_f32_16x16x32_bf16 v[36:39], v[176:179], v[210:213], v[36:39]
	v_mfma_f32_16x16x32_bf16 v[32:35], v[190:193], v[210:213], v[32:35]
	v_mfma_f32_16x16x32_bf16 v[20:23], v[176:179], v[218:221], v[20:23]
	v_mfma_f32_16x16x32_bf16 v[16:19], v[190:193], v[218:221], v[16:19]
	v_mfma_f32_16x16x32_bf16 v[4:7], v[176:179], v[226:229], v[4:7]
	v_mfma_f32_16x16x32_bf16 v[0:3], v[190:193], v[226:229], v[0:3]
	v_mfma_f32_16x16x32_bf16 v[52:55], v[186:189], v[206:209], v[52:55]
	v_mfma_f32_16x16x32_bf16 v[48:51], v[194:197], v[206:209], v[48:51]
	v_mfma_f32_16x16x32_bf16 v[36:39], v[186:189], v[214:217], v[36:39]
	v_mfma_f32_16x16x32_bf16 v[32:35], v[194:197], v[214:217], v[32:35]
	v_mfma_f32_16x16x32_bf16 v[20:23], v[186:189], v[222:225], v[20:23]
	v_mfma_f32_16x16x32_bf16 v[16:19], v[194:197], v[222:225], v[16:19]
	v_mfma_f32_16x16x32_bf16 v[4:7], v[186:189], v[230:233], v[4:7]
	v_mfma_f32_16x16x32_bf16 v[0:3], v[194:197], v[230:233], v[0:3]
	s_setprio 0
	s_barrier
	s_add_i32 s58, 0, 0x18000
	s_add_i32 s59, 0, 0x1c000
	v_add_u32_e32 v140, s58, v180
	v_add_u32_e32 v185, s59, v180
	ds_read_b128 v[128:131], v140
	ds_read_b128 v[132:135], v140 offset:1024
	ds_read_b128 v[136:139], v140 offset:2048
	ds_read_b128 v[140:143], v140 offset:3072
	ds_read_b128 v[176:179], v185
	ds_read_b128 v[186:189], v185 offset:1024
	ds_read_b128 v[190:193], v185 offset:2048
	ds_read_b128 v[194:197], v185 offset:3072
	s_add_u32 s14, s24, 0xb0000
	s_addc_u32 s15, s25, 0
	s_mov_b32 m0, s39
	v_lshl_add_u64 v[238:239], s[14:15], 0, v[150:151]
	ds_read_b128 v[202:205], v184 offset:32768
	ds_read_b128 v[206:209], v184 offset:33792
	ds_read_b128 v[210:213], v184 offset:34816
	ds_read_b128 v[214:217], v184 offset:35840
	ds_read_b128 v[218:221], v184 offset:36864
	ds_read_b128 v[222:225], v184 offset:37888
	ds_read_b128 v[226:229], v184 offset:38912
	ds_read_b128 v[230:233], v184 offset:39936
	global_load_lds_dwordx4 v[238:239], off
	v_lshl_add_u64 v[238:239], s[14:15], 0, v[146:147]
	s_mov_b32 m0, s40
	s_nop 0
	global_load_lds_dwordx4 v[238:239], off
	s_waitcnt vmcnt(8)
	s_waitcnt lgkmcnt(0)
	s_barrier
	s_setprio 1
	s_waitcnt lgkmcnt(0)
	v_mfma_f32_16x16x32_bf16 v[124:127], v[128:131], v[202:205], v[124:127]
	v_mfma_f32_16x16x32_bf16 v[120:123], v[136:139], v[202:205], v[120:123]
	v_mfma_f32_16x16x32_bf16 v[116:119], v[128:131], v[210:213], v[116:119]
	v_mfma_f32_16x16x32_bf16 v[112:115], v[136:139], v[210:213], v[112:115]
	v_mfma_f32_16x16x32_bf16 v[92:95], v[128:131], v[218:221], v[92:95]
	v_mfma_f32_16x16x32_bf16 v[88:91], v[136:139], v[218:221], v[88:91]
	v_mfma_f32_16x16x32_bf16 v[76:79], v[128:131], v[226:229], v[76:79]
	v_mfma_f32_16x16x32_bf16 v[72:75], v[136:139], v[226:229], v[72:75]
	v_mfma_f32_16x16x32_bf16 v[124:127], v[132:135], v[206:209], v[124:127]
	v_mfma_f32_16x16x32_bf16 v[120:123], v[140:143], v[206:209], v[120:123]
	v_mfma_f32_16x16x32_bf16 v[116:119], v[132:135], v[214:217], v[116:119]
	v_mfma_f32_16x16x32_bf16 v[112:115], v[140:143], v[214:217], v[112:115]
	v_mfma_f32_16x16x32_bf16 v[92:95], v[132:135], v[222:225], v[92:95]
	v_mfma_f32_16x16x32_bf16 v[88:91], v[140:143], v[222:225], v[88:91]
	v_mfma_f32_16x16x32_bf16 v[76:79], v[132:135], v[230:233], v[76:79]
	v_mfma_f32_16x16x32_bf16 v[72:75], v[140:143], v[230:233], v[72:75]
	s_setprio 0
	s_setprio 1
	v_mfma_f32_16x16x32_bf16 v[108:111], v[176:179], v[202:205], v[108:111]
	v_mfma_f32_16x16x32_bf16 v[104:107], v[190:193], v[202:205], v[104:107]
	v_mfma_f32_16x16x32_bf16 v[100:103], v[176:179], v[210:213], v[100:103]
	v_mfma_f32_16x16x32_bf16 v[96:99], v[190:193], v[210:213], v[96:99]
	v_mfma_f32_16x16x32_bf16 v[84:87], v[176:179], v[218:221], v[84:87]
	v_mfma_f32_16x16x32_bf16 v[80:83], v[190:193], v[218:221], v[80:83]
	v_mfma_f32_16x16x32_bf16 v[68:71], v[176:179], v[226:229], v[68:71]
	v_mfma_f32_16x16x32_bf16 v[64:67], v[190:193], v[226:229], v[64:67]
	v_mfma_f32_16x16x32_bf16 v[108:111], v[186:189], v[206:209], v[108:111]
	v_mfma_f32_16x16x32_bf16 v[104:107], v[194:197], v[206:209], v[104:107]
	v_mfma_f32_16x16x32_bf16 v[100:103], v[186:189], v[214:217], v[100:103]
	v_mfma_f32_16x16x32_bf16 v[96:99], v[194:197], v[214:217], v[96:99]
	v_mfma_f32_16x16x32_bf16 v[84:87], v[186:189], v[222:225], v[84:87]
	v_mfma_f32_16x16x32_bf16 v[80:83], v[194:197], v[222:225], v[80:83]
	v_mfma_f32_16x16x32_bf16 v[68:71], v[186:189], v[230:233], v[68:71]
	v_mfma_f32_16x16x32_bf16 v[64:67], v[194:197], v[230:233], v[64:67]
	s_setprio 0
	s_barrier
	s_add_i32 s14, s58, s34
	v_lshl_add_u64 v[198:199], v[198:199], 0, s[8:9]
	s_mov_b32 m0, s14
	ds_read_b128 v[202:205], v184 offset:49152
	ds_read_b128 v[206:209], v184 offset:50176
	ds_read_b128 v[210:213], v184 offset:51200
	ds_read_b128 v[214:217], v184 offset:52224
	ds_read_b128 v[218:221], v184 offset:53248
	ds_read_b128 v[222:225], v184 offset:54272
	ds_read_b128 v[226:229], v184 offset:55296
	ds_read_b128 v[230:233], v184 offset:56320
	global_load_lds_dwordx4 v[198:199], off
	s_add_i32 m0, s14, 0x2000
	s_add_u32 s14, s18, 0xb0080
	v_lshl_add_u64 v[198:199], v[200:201], 0, s[8:9]
	s_addc_u32 s15, s19, 0
	s_add_i32 s18, s59, s34
	global_load_lds_dwordx4 v[198:199], off
	v_lshl_add_u64 v[198:199], s[14:15], 0, v[148:149]
	s_mov_b32 m0, s18
	s_nop 0
	global_load_lds_dwordx4 v[198:199], off
	v_lshl_add_u64 v[198:199], s[14:15], 0, v[144:145]
	s_add_i32 m0, s18, 0x2000
	s_nop 0
	global_load_lds_dwordx4 v[198:199], off
	v_lshl_add_u64 v[198:199], v[234:235], 0, s[8:9]
	s_mov_b32 m0, s46
	s_nop 0
	global_load_lds_dwordx4 v[198:199], off
	v_lshl_add_u64 v[198:199], v[236:237], 0, s[8:9]
	s_mov_b32 m0, s47
	s_nop 0
	global_load_lds_dwordx4 v[198:199], off
	s_add_i32 s57, s57, 2
	s_add_u32 s55, s55, 0x100
	s_addc_u32 s56, s56, 0
	s_cmp_gt_u32 s57, 41
	s_mov_b64 s[14:15], s[16:17]
	s_waitcnt vmcnt(8)
	s_waitcnt lgkmcnt(0)
	s_barrier
	s_setprio 1
	s_waitcnt lgkmcnt(0)
	v_mfma_f32_16x16x32_bf16 v[60:63], v[128:131], v[202:205], v[60:63]
	v_mfma_f32_16x16x32_bf16 v[56:59], v[136:139], v[202:205], v[56:59]
	v_mfma_f32_16x16x32_bf16 v[44:47], v[128:131], v[210:213], v[44:47]
	v_mfma_f32_16x16x32_bf16 v[40:43], v[136:139], v[210:213], v[40:43]
	v_mfma_f32_16x16x32_bf16 v[28:31], v[128:131], v[218:221], v[28:31]
	v_mfma_f32_16x16x32_bf16 v[24:27], v[136:139], v[218:221], v[24:27]
	v_mfma_f32_16x16x32_bf16 v[12:15], v[128:131], v[226:229], v[12:15]
	v_mfma_f32_16x16x32_bf16 v[8:11], v[136:139], v[226:229], v[8:11]
	v_mfma_f32_16x16x32_bf16 v[60:63], v[132:135], v[206:209], v[60:63]
	v_mfma_f32_16x16x32_bf16 v[56:59], v[140:143], v[206:209], v[56:59]
	v_mfma_f32_16x16x32_bf16 v[44:47], v[132:135], v[214:217], v[44:47]
	v_mfma_f32_16x16x32_bf16 v[40:43], v[140:143], v[214:217], v[40:43]
	v_mfma_f32_16x16x32_bf16 v[28:31], v[132:135], v[222:225], v[28:31]
	v_mfma_f32_16x16x32_bf16 v[24:27], v[140:143], v[222:225], v[24:27]
	v_mfma_f32_16x16x32_bf16 v[12:15], v[132:135], v[230:233], v[12:15]
	v_mfma_f32_16x16x32_bf16 v[8:11], v[140:143], v[230:233], v[8:11]
	s_setprio 0
	s_setprio 1
	v_mfma_f32_16x16x32_bf16 v[52:55], v[176:179], v[202:205], v[52:55]
	v_mfma_f32_16x16x32_bf16 v[48:51], v[190:193], v[202:205], v[48:51]
	v_mfma_f32_16x16x32_bf16 v[36:39], v[176:179], v[210:213], v[36:39]
	v_mfma_f32_16x16x32_bf16 v[32:35], v[190:193], v[210:213], v[32:35]
	v_mfma_f32_16x16x32_bf16 v[20:23], v[176:179], v[218:221], v[20:23]
	v_mfma_f32_16x16x32_bf16 v[16:19], v[190:193], v[218:221], v[16:19]
	v_mfma_f32_16x16x32_bf16 v[4:7], v[176:179], v[226:229], v[4:7]
	v_mfma_f32_16x16x32_bf16 v[0:3], v[190:193], v[226:229], v[0:3]
	v_mfma_f32_16x16x32_bf16 v[52:55], v[186:189], v[206:209], v[52:55]
	v_mfma_f32_16x16x32_bf16 v[48:51], v[194:197], v[206:209], v[48:51]
	v_mfma_f32_16x16x32_bf16 v[36:39], v[186:189], v[214:217], v[36:39]
	v_mfma_f32_16x16x32_bf16 v[32:35], v[194:197], v[214:217], v[32:35]
	v_mfma_f32_16x16x32_bf16 v[20:23], v[186:189], v[222:225], v[20:23]
	v_mfma_f32_16x16x32_bf16 v[16:19], v[194:197], v[222:225], v[16:19]
	v_mfma_f32_16x16x32_bf16 v[4:7], v[186:189], v[230:233], v[4:7]
	v_mfma_f32_16x16x32_bf16 v[0:3], v[194:197], v[230:233], v[0:3]
	s_setprio 0
	s_barrier
	s_cbranch_scc0 .LBB0_648
	s_and_b64 vcc, exec, s[10:11]
	s_cbranch_vccz .LBB0_651
	s_barrier

.LBB0_802:
	ds_read_b128 v[156:159], v152
	ds_read_b128 v[160:163], v152 offset:1024
	ds_read_b128 v[164:167], v152 offset:2048
	ds_read_b128 v[168:171], v152 offset:3072
	ds_read_b128 v[172:175], v153
	ds_read_b128 v[176:179], v153 offset:1024
	ds_read_b128 v[180:183], v153 offset:2048
	ds_read_b128 v[184:187], v153 offset:3072
	s_add_u32 s42, s38, 0xfffc0080
	s_addc_u32 s43, s39, -1
	s_cmp_eq_u32 s66, 12
	s_cselect_b32 s45, s7, s43
	s_cselect_b32 s44, s31, s42
	s_cselect_b32 s43, s29, s65
	s_cselect_b32 s42, s33, s64
	v_lshl_add_u64 v[144:145], s[38:39], 0, v[136:137]
	s_add_i32 m0, s41, 0xc000
	ds_read_b128 v[188:191], v154
	ds_read_b128 v[192:195], v154 offset:1024
	ds_read_b128 v[196:199], v154 offset:2048
	ds_read_b128 v[202:205], v154 offset:3072
	ds_read_b128 v[206:209], v154 offset:4096
	ds_read_b128 v[210:213], v154 offset:5120
	ds_read_b128 v[214:217], v154 offset:6144
	ds_read_b128 v[218:221], v154 offset:7168
	global_load_lds_dwordx4 v[144:145], off
	v_lshl_add_u64 v[144:145], s[38:39], 0, v[138:139]
	s_add_i32 m0, s41, 0xe000
	s_nop 0
	global_load_lds_dwordx4 v[144:145], off
	s_waitcnt vmcnt(8)
	s_waitcnt lgkmcnt(0)
	s_barrier
	s_setprio 1
	s_waitcnt lgkmcnt(0)
	v_mfma_f32_16x16x32_bf16 v[124:127], v[156:159], v[188:191], v[124:127]
	v_mfma_f32_16x16x32_bf16 v[120:123], v[164:167], v[188:191], v[120:123]
	v_mfma_f32_16x16x32_bf16 v[108:111], v[156:159], v[196:199], v[108:111]
	v_mfma_f32_16x16x32_bf16 v[104:107], v[164:167], v[196:199], v[104:107]
	v_mfma_f32_16x16x32_bf16 v[92:95], v[156:159], v[206:209], v[92:95]
	v_mfma_f32_16x16x32_bf16 v[88:91], v[164:167], v[206:209], v[88:91]
	v_mfma_f32_16x16x32_bf16 v[76:79], v[156:159], v[214:217], v[76:79]
	v_mfma_f32_16x16x32_bf16 v[72:75], v[164:167], v[214:217], v[72:75]
	v_mfma_f32_16x16x32_bf16 v[124:127], v[160:163], v[192:195], v[124:127]
	v_mfma_f32_16x16x32_bf16 v[120:123], v[168:171], v[192:195], v[120:123]
	v_mfma_f32_16x16x32_bf16 v[108:111], v[160:163], v[202:205], v[108:111]
	v_mfma_f32_16x16x32_bf16 v[104:107], v[168:171], v[202:205], v[104:107]
	v_mfma_f32_16x16x32_bf16 v[92:95], v[160:163], v[210:213], v[92:95]
	v_mfma_f32_16x16x32_bf16 v[88:91], v[168:171], v[210:213], v[88:91]
	v_mfma_f32_16x16x32_bf16 v[76:79], v[160:163], v[218:221], v[76:79]
	v_mfma_f32_16x16x32_bf16 v[72:75], v[168:171], v[218:221], v[72:75]
	s_setprio 0
	s_setprio 1
	v_mfma_f32_16x16x32_bf16 v[116:119], v[172:175], v[188:191], v[116:119]
	v_mfma_f32_16x16x32_bf16 v[112:115], v[180:183], v[188:191], v[112:115]
	v_mfma_f32_16x16x32_bf16 v[100:103], v[172:175], v[196:199], v[100:103]
	v_mfma_f32_16x16x32_bf16 v[96:99], v[180:183], v[196:199], v[96:99]
	v_mfma_f32_16x16x32_bf16 v[84:87], v[172:175], v[206:209], v[84:87]
	v_mfma_f32_16x16x32_bf16 v[80:83], v[180:183], v[206:209], v[80:83]
	v_mfma_f32_16x16x32_bf16 v[68:71], v[172:175], v[214:217], v[68:71]
	v_mfma_f32_16x16x32_bf16 v[64:67], v[180:183], v[214:217], v[64:67]
	v_mfma_f32_16x16x32_bf16 v[116:119], v[176:179], v[192:195], v[116:119]
	v_mfma_f32_16x16x32_bf16 v[112:115], v[184:187], v[192:195], v[112:115]
	v_mfma_f32_16x16x32_bf16 v[100:103], v[176:179], v[202:205], v[100:103]
	v_mfma_f32_16x16x32_bf16 v[96:99], v[184:187], v[202:205], v[96:99]
	v_mfma_f32_16x16x32_bf16 v[84:87], v[176:179], v[210:213], v[84:87]
	v_mfma_f32_16x16x32_bf16 v[80:83], v[184:187], v[210:213], v[80:83]
	v_mfma_f32_16x16x32_bf16 v[68:71], v[176:179], v[218:221], v[68:71]
	v_mfma_f32_16x16x32_bf16 v[64:67], v[184:187], v[218:221], v[64:67]
	s_setprio 0
	s_barrier
	s_add_i32 s67, s62, s50
	v_lshl_add_u64 v[144:145], s[42:43], 0, v[130:131]
	s_mov_b32 m0, s67
	ds_read_b128 v[188:191], v154 offset:16384
	ds_read_b128 v[192:195], v154 offset:17408
	ds_read_b128 v[196:199], v154 offset:18432
	ds_read_b128 v[202:205], v154 offset:19456
	ds_read_b128 v[206:209], v154 offset:20480
	ds_read_b128 v[210:213], v154 offset:21504
	ds_read_b128 v[214:217], v154 offset:22528
	ds_read_b128 v[218:221], v154 offset:23552
	global_load_lds_dwordx4 v[144:145], off
	s_add_i32 m0, s67, 0x2000
	s_add_u32 s68, s42, 0x40000
	v_lshl_add_u64 v[200:201], s[42:43], 0, v[134:135]
	s_addc_u32 s69, s43, 0
	s_add_i32 s67, s63, s50
	global_load_lds_dwordx4 v[200:201], off
	v_lshl_add_u64 v[222:223], s[68:69], 0, v[130:131]
	s_mov_b32 m0, s67
	v_lshl_add_u64 v[224:225], s[44:45], 0, v[132:133]
	global_load_lds_dwordx4 v[222:223], off
	v_lshl_add_u64 v[222:223], s[68:69], 0, v[134:135]
	s_add_i32 m0, s67, 0x2000
	s_nop 0
	global_load_lds_dwordx4 v[222:223], off
	v_lshl_add_u64 v[222:223], s[44:45], 0, v[128:129]
	s_mov_b32 m0, s41
	s_nop 0
	global_load_lds_dwordx4 v[222:223], off
	s_mov_b32 m0, s51
	s_nop 0
	global_load_lds_dwordx4 v[224:225], off
	s_waitcnt vmcnt(8)
	s_waitcnt lgkmcnt(0)
	s_barrier
	s_setprio 1
	s_waitcnt lgkmcnt(0)
	v_mfma_f32_16x16x32_bf16 v[60:63], v[156:159], v[188:191], v[60:63]
	v_mfma_f32_16x16x32_bf16 v[56:59], v[164:167], v[188:191], v[56:59]
	v_mfma_f32_16x16x32_bf16 v[44:47], v[156:159], v[196:199], v[44:47]
	v_mfma_f32_16x16x32_bf16 v[40:43], v[164:167], v[196:199], v[40:43]
	v_mfma_f32_16x16x32_bf16 v[28:31], v[156:159], v[206:209], v[28:31]
	v_mfma_f32_16x16x32_bf16 v[24:27], v[164:167], v[206:209], v[24:27]
	v_mfma_f32_16x16x32_bf16 v[12:15], v[156:159], v[214:217], v[12:15]
	v_mfma_f32_16x16x32_bf16 v[8:11], v[164:167], v[214:217], v[8:11]
	v_mfma_f32_16x16x32_bf16 v[60:63], v[160:163], v[192:195], v[60:63]
	v_mfma_f32_16x16x32_bf16 v[56:59], v[168:171], v[192:195], v[56:59]
	v_mfma_f32_16x16x32_bf16 v[44:47], v[160:163], v[202:205], v[44:47]
	v_mfma_f32_16x16x32_bf16 v[40:43], v[168:171], v[202:205], v[40:43]
	v_mfma_f32_16x16x32_bf16 v[28:31], v[160:163], v[210:213], v[28:31]
	v_mfma_f32_16x16x32_bf16 v[24:27], v[168:171], v[210:213], v[24:27]
	v_mfma_f32_16x16x32_bf16 v[12:15], v[160:163], v[218:221], v[12:15]
	v_mfma_f32_16x16x32_bf16 v[8:11], v[168:171], v[218:221], v[8:11]
	s_setprio 0
	s_setprio 1
	v_mfma_f32_16x16x32_bf16 v[52:55], v[172:175], v[188:191], v[52:55]
	v_mfma_f32_16x16x32_bf16 v[48:51], v[180:183], v[188:191], v[48:51]
	v_mfma_f32_16x16x32_bf16 v[36:39], v[172:175], v[196:199], v[36:39]
	v_mfma_f32_16x16x32_bf16 v[32:35], v[180:183], v[196:199], v[32:35]
	v_mfma_f32_16x16x32_bf16 v[20:23], v[172:175], v[206:209], v[20:23]
	v_mfma_f32_16x16x32_bf16 v[16:19], v[180:183], v[206:209], v[16:19]
	v_mfma_f32_16x16x32_bf16 v[4:7], v[172:175], v[214:217], v[4:7]
	v_mfma_f32_16x16x32_bf16 v[0:3], v[180:183], v[214:217], v[0:3]
	v_mfma_f32_16x16x32_bf16 v[52:55], v[176:179], v[192:195], v[52:55]
	v_mfma_f32_16x16x32_bf16 v[48:51], v[184:187], v[192:195], v[48:51]
	v_mfma_f32_16x16x32_bf16 v[36:39], v[176:179], v[202:205], v[36:39]
	v_mfma_f32_16x16x32_bf16 v[32:35], v[184:187], v[202:205], v[32:35]
	v_mfma_f32_16x16x32_bf16 v[20:23], v[176:179], v[210:213], v[20:23]
	v_mfma_f32_16x16x32_bf16 v[16:19], v[184:187], v[210:213], v[16:19]
	v_mfma_f32_16x16x32_bf16 v[4:7], v[176:179], v[218:221], v[4:7]
	v_mfma_f32_16x16x32_bf16 v[0:3], v[184:187], v[218:221], v[0:3]
	s_setprio 0
	s_barrier
	s_add_i32 s67, 0, 0x18000
	s_add_i32 s68, 0, 0x1c000
	v_add_u32_e32 v168, s67, v147
	v_add_u32_e32 v184, s68, v147
	ds_read_b128 v[156:159], v168
	ds_read_b128 v[160:163], v168 offset:1024
	ds_read_b128 v[164:167], v168 offset:2048
	ds_read_b128 v[168:171], v168 offset:3072
	ds_read_b128 v[172:175], v184
	ds_read_b128 v[176:179], v184 offset:1024
	ds_read_b128 v[180:183], v184 offset:2048
	ds_read_b128 v[184:187], v184 offset:3072
	s_add_u32 s44, s44, 0x40000
	s_addc_u32 s45, s45, 0
	s_mov_b32 m0, s52
	v_lshl_add_u64 v[226:227], s[44:45], 0, v[128:129]
	ds_read_b128 v[188:191], v154 offset:32768
	ds_read_b128 v[192:195], v154 offset:33792
	ds_read_b128 v[196:199], v154 offset:34816
	ds_read_b128 v[202:205], v154 offset:35840
	ds_read_b128 v[206:209], v154 offset:36864
	ds_read_b128 v[210:213], v154 offset:37888
	ds_read_b128 v[214:217], v154 offset:38912
	ds_read_b128 v[218:221], v154 offset:39936
	global_load_lds_dwordx4 v[226:227], off
	v_lshl_add_u64 v[226:227], s[44:45], 0, v[132:133]
	s_mov_b32 m0, s53
	s_nop 0
	global_load_lds_dwordx4 v[226:227], off
	s_waitcnt vmcnt(8)
	s_waitcnt lgkmcnt(0)
	s_barrier
	s_setprio 1
	s_waitcnt lgkmcnt(0)
	v_mfma_f32_16x16x32_bf16 v[124:127], v[156:159], v[188:191], v[124:127]
	v_mfma_f32_16x16x32_bf16 v[120:123], v[164:167], v[188:191], v[120:123]
	v_mfma_f32_16x16x32_bf16 v[108:111], v[156:159], v[196:199], v[108:111]
	v_mfma_f32_16x16x32_bf16 v[104:107], v[164:167], v[196:199], v[104:107]
	v_mfma_f32_16x16x32_bf16 v[92:95], v[156:159], v[206:209], v[92:95]
	v_mfma_f32_16x16x32_bf16 v[88:91], v[164:167], v[206:209], v[88:91]
	v_mfma_f32_16x16x32_bf16 v[76:79], v[156:159], v[214:217], v[76:79]
	v_mfma_f32_16x16x32_bf16 v[72:75], v[164:167], v[214:217], v[72:75]
	v_mfma_f32_16x16x32_bf16 v[124:127], v[160:163], v[192:195], v[124:127]
	v_mfma_f32_16x16x32_bf16 v[120:123], v[168:171], v[192:195], v[120:123]
	v_mfma_f32_16x16x32_bf16 v[108:111], v[160:163], v[202:205], v[108:111]
	v_mfma_f32_16x16x32_bf16 v[104:107], v[168:171], v[202:205], v[104:107]
	v_mfma_f32_16x16x32_bf16 v[92:95], v[160:163], v[210:213], v[92:95]
	v_mfma_f32_16x16x32_bf16 v[88:91], v[168:171], v[210:213], v[88:91]
	v_mfma_f32_16x16x32_bf16 v[76:79], v[160:163], v[218:221], v[76:79]
	v_mfma_f32_16x16x32_bf16 v[72:75], v[168:171], v[218:221], v[72:75]
	s_setprio 0
	s_setprio 1
	v_mfma_f32_16x16x32_bf16 v[116:119], v[172:175], v[188:191], v[116:119]
	v_mfma_f32_16x16x32_bf16 v[112:115], v[180:183], v[188:191], v[112:115]
	v_mfma_f32_16x16x32_bf16 v[100:103], v[172:175], v[196:199], v[100:103]
	v_mfma_f32_16x16x32_bf16 v[96:99], v[180:183], v[196:199], v[96:99]
	v_mfma_f32_16x16x32_bf16 v[84:87], v[172:175], v[206:209], v[84:87]
	v_mfma_f32_16x16x32_bf16 v[80:83], v[180:183], v[206:209], v[80:83]
	v_mfma_f32_16x16x32_bf16 v[68:71], v[172:175], v[214:217], v[68:71]
	v_mfma_f32_16x16x32_bf16 v[64:67], v[180:183], v[214:217], v[64:67]
	v_mfma_f32_16x16x32_bf16 v[116:119], v[176:179], v[192:195], v[116:119]
	v_mfma_f32_16x16x32_bf16 v[112:115], v[184:187], v[192:195], v[112:115]
	v_mfma_f32_16x16x32_bf16 v[100:103], v[176:179], v[202:205], v[100:103]
	v_mfma_f32_16x16x32_bf16 v[96:99], v[184:187], v[202:205], v[96:99]
	v_mfma_f32_16x16x32_bf16 v[84:87], v[176:179], v[210:213], v[84:87]
	v_mfma_f32_16x16x32_bf16 v[80:83], v[184:187], v[210:213], v[80:83]
	v_mfma_f32_16x16x32_bf16 v[68:71], v[176:179], v[218:221], v[68:71]
	v_mfma_f32_16x16x32_bf16 v[64:67], v[184:187], v[218:221], v[64:67]
	s_setprio 0
	s_barrier
	s_add_i32 s44, s67, s50
	v_lshl_add_u64 v[144:145], v[144:145], 0, s[18:19]
	s_mov_b32 m0, s44
	ds_read_b128 v[188:191], v154 offset:49152
	ds_read_b128 v[192:195], v154 offset:50176
	ds_read_b128 v[196:199], v154 offset:51200
	ds_read_b128 v[202:205], v154 offset:52224
	ds_read_b128 v[206:209], v154 offset:53248
	ds_read_b128 v[210:213], v154 offset:54272
	ds_read_b128 v[214:217], v154 offset:55296
	ds_read_b128 v[218:221], v154 offset:56320
	global_load_lds_dwordx4 v[144:145], off
	s_add_i32 m0, s44, 0x2000
	s_add_u32 s42, s42, 0x40080
	v_lshl_add_u64 v[144:145], v[200:201], 0, s[18:19]
	s_addc_u32 s43, s43, 0
	s_add_i32 s44, s68, s50
	global_load_lds_dwordx4 v[144:145], off
	v_lshl_add_u64 v[144:145], s[42:43], 0, v[130:131]
	s_mov_b32 m0, s44
	s_nop 0
	global_load_lds_dwordx4 v[144:145], off
	v_lshl_add_u64 v[144:145], s[42:43], 0, v[134:135]
	s_add_i32 m0, s44, 0x2000
	s_nop 0
	global_load_lds_dwordx4 v[144:145], off
	v_lshl_add_u64 v[144:145], v[222:223], 0, s[18:19]
	s_mov_b32 m0, s56
	s_nop 0
	global_load_lds_dwordx4 v[144:145], off
	v_lshl_add_u64 v[144:145], v[224:225], 0, s[18:19]
	s_mov_b32 m0, s57
	s_nop 0
	global_load_lds_dwordx4 v[144:145], off
	s_add_i32 s66, s66, 2
	s_add_u32 s38, s38, 0x100
	s_addc_u32 s39, s39, 0
	s_add_u32 s64, s64, 0x100
	s_addc_u32 s65, s65, 0
	s_cmp_gt_u32 s66, 13
	s_waitcnt vmcnt(8)
	s_waitcnt lgkmcnt(0)
	s_barrier
	s_setprio 1
	s_waitcnt lgkmcnt(0)
	v_mfma_f32_16x16x32_bf16 v[60:63], v[156:159], v[188:191], v[60:63]
	v_mfma_f32_16x16x32_bf16 v[56:59], v[164:167], v[188:191], v[56:59]
	v_mfma_f32_16x16x32_bf16 v[44:47], v[156:159], v[196:199], v[44:47]
	v_mfma_f32_16x16x32_bf16 v[40:43], v[164:167], v[196:199], v[40:43]
	v_mfma_f32_16x16x32_bf16 v[28:31], v[156:159], v[206:209], v[28:31]
	v_mfma_f32_16x16x32_bf16 v[24:27], v[164:167], v[206:209], v[24:27]
	v_mfma_f32_16x16x32_bf16 v[12:15], v[156:159], v[214:217], v[12:15]
	v_mfma_f32_16x16x32_bf16 v[8:11], v[164:167], v[214:217], v[8:11]
	v_mfma_f32_16x16x32_bf16 v[60:63], v[160:163], v[192:195], v[60:63]
	v_mfma_f32_16x16x32_bf16 v[56:59], v[168:171], v[192:195], v[56:59]
	v_mfma_f32_16x16x32_bf16 v[44:47], v[160:163], v[202:205], v[44:47]
	v_mfma_f32_16x16x32_bf16 v[40:43], v[168:171], v[202:205], v[40:43]
	v_mfma_f32_16x16x32_bf16 v[28:31], v[160:163], v[210:213], v[28:31]
	v_mfma_f32_16x16x32_bf16 v[24:27], v[168:171], v[210:213], v[24:27]
	v_mfma_f32_16x16x32_bf16 v[12:15], v[160:163], v[218:221], v[12:15]
	v_mfma_f32_16x16x32_bf16 v[8:11], v[168:171], v[218:221], v[8:11]
	s_setprio 0
	s_setprio 1
	v_mfma_f32_16x16x32_bf16 v[52:55], v[172:175], v[188:191], v[52:55]
	v_mfma_f32_16x16x32_bf16 v[48:51], v[180:183], v[188:191], v[48:51]
	v_mfma_f32_16x16x32_bf16 v[36:39], v[172:175], v[196:199], v[36:39]
	v_mfma_f32_16x16x32_bf16 v[32:35], v[180:183], v[196:199], v[32:35]
	v_mfma_f32_16x16x32_bf16 v[20:23], v[172:175], v[206:209], v[20:23]
	v_mfma_f32_16x16x32_bf16 v[16:19], v[180:183], v[206:209], v[16:19]
	v_mfma_f32_16x16x32_bf16 v[4:7], v[172:175], v[214:217], v[4:7]
	v_mfma_f32_16x16x32_bf16 v[0:3], v[180:183], v[214:217], v[0:3]
	v_mfma_f32_16x16x32_bf16 v[52:55], v[176:179], v[192:195], v[52:55]
	v_mfma_f32_16x16x32_bf16 v[48:51], v[184:187], v[192:195], v[48:51]
	v_mfma_f32_16x16x32_bf16 v[36:39], v[176:179], v[202:205], v[36:39]
	v_mfma_f32_16x16x32_bf16 v[32:35], v[184:187], v[202:205], v[32:35]
	v_mfma_f32_16x16x32_bf16 v[20:23], v[176:179], v[210:213], v[20:23]
	v_mfma_f32_16x16x32_bf16 v[16:19], v[184:187], v[210:213], v[16:19]
	v_mfma_f32_16x16x32_bf16 v[4:7], v[176:179], v[218:221], v[4:7]
	v_mfma_f32_16x16x32_bf16 v[0:3], v[184:187], v[218:221], v[0:3]
	s_setprio 0
	s_barrier
	s_cbranch_scc0 .LBB0_802
	s_and_b64 vcc, exec, s[24:25]
	s_cbranch_vccz .LBB0_805
	s_barrier

.LBB0_1077:
	ds_read_b128 v[60:63], v195
	ds_read_b128 v[64:67], v195 offset:1024
	ds_read_b128 v[68:71], v195 offset:2048
	ds_read_b128 v[76:79], v195 offset:3072
	ds_read_b128 v[144:147], v196
	ds_read_b128 v[148:151], v196 offset:1024
	ds_read_b128 v[152:155], v196 offset:2048
	ds_read_b128 v[172:175], v196 offset:3072
	s_add_u32 s30, s28, 0xfffc0080
	s_addc_u32 s31, s29, -1
	s_cmp_eq_u32 s58, 12
	s_cselect_b32 s35, s17, s31
	s_cselect_b32 s34, s33, s30
	s_cselect_b32 s31, s15, s57
	s_cselect_b32 s30, s55, s56
	v_lshl_add_u64 v[198:199], s[28:29], 0, v[164:165]
	s_add_i32 m0, s41, 0xc000
	ds_read_b128 v[176:179], v197
	ds_read_b128 v[180:183], v197 offset:1024
	ds_read_b128 v[184:187], v197 offset:2048
	ds_read_b128 v[188:191], v197 offset:3072
	ds_read_b128 v[202:205], v197 offset:4096
	ds_read_b128 v[206:209], v197 offset:5120
	ds_read_b128 v[210:213], v197 offset:6144
	ds_read_b128 v[214:217], v197 offset:7168
	global_load_lds_dwordx4 v[198:199], off
	v_lshl_add_u64 v[198:199], s[28:29], 0, v[166:167]
	s_add_i32 m0, s41, 0xe000
	s_nop 0
	global_load_lds_dwordx4 v[198:199], off
	s_waitcnt vmcnt(8)
	s_waitcnt lgkmcnt(0)
	s_barrier
	s_setprio 1
	s_waitcnt lgkmcnt(0)
	v_mfma_f32_16x16x32_bf16 v[140:143], v[60:63], v[176:179], v[140:143]
	v_mfma_f32_16x16x32_bf16 v[136:139], v[68:71], v[176:179], v[136:139]
	v_mfma_f32_16x16x32_bf16 v[124:127], v[60:63], v[184:187], v[124:127]
	v_mfma_f32_16x16x32_bf16 v[120:123], v[68:71], v[184:187], v[120:123]
	v_mfma_f32_16x16x32_bf16 v[108:111], v[60:63], v[202:205], v[108:111]
	v_mfma_f32_16x16x32_bf16 v[104:107], v[68:71], v[202:205], v[104:107]
	v_mfma_f32_16x16x32_bf16 v[92:95], v[60:63], v[210:213], v[92:95]
	v_mfma_f32_16x16x32_bf16 v[88:91], v[68:71], v[210:213], v[88:91]
	v_mfma_f32_16x16x32_bf16 v[140:143], v[64:67], v[180:183], v[140:143]
	v_mfma_f32_16x16x32_bf16 v[136:139], v[76:79], v[180:183], v[136:139]
	v_mfma_f32_16x16x32_bf16 v[124:127], v[64:67], v[188:191], v[124:127]
	v_mfma_f32_16x16x32_bf16 v[120:123], v[76:79], v[188:191], v[120:123]
	v_mfma_f32_16x16x32_bf16 v[108:111], v[64:67], v[206:209], v[108:111]
	v_mfma_f32_16x16x32_bf16 v[104:107], v[76:79], v[206:209], v[104:107]
	v_mfma_f32_16x16x32_bf16 v[92:95], v[64:67], v[214:217], v[92:95]
	v_mfma_f32_16x16x32_bf16 v[88:91], v[76:79], v[214:217], v[88:91]
	s_setprio 0
	s_setprio 1
	v_mfma_f32_16x16x32_bf16 v[132:135], v[144:147], v[176:179], v[132:135]
	v_mfma_f32_16x16x32_bf16 v[128:131], v[152:155], v[176:179], v[128:131]
	v_mfma_f32_16x16x32_bf16 v[116:119], v[144:147], v[184:187], v[116:119]
	v_mfma_f32_16x16x32_bf16 v[112:115], v[152:155], v[184:187], v[112:115]
	v_mfma_f32_16x16x32_bf16 v[100:103], v[144:147], v[202:205], v[100:103]
	v_mfma_f32_16x16x32_bf16 v[96:99], v[152:155], v[202:205], v[96:99]
	v_mfma_f32_16x16x32_bf16 v[84:87], v[144:147], v[210:213], v[84:87]
	v_mfma_f32_16x16x32_bf16 v[80:83], v[152:155], v[210:213], v[80:83]
	v_mfma_f32_16x16x32_bf16 v[132:135], v[148:151], v[180:183], v[132:135]
	v_mfma_f32_16x16x32_bf16 v[128:131], v[172:175], v[180:183], v[128:131]
	v_mfma_f32_16x16x32_bf16 v[116:119], v[148:151], v[188:191], v[116:119]
	v_mfma_f32_16x16x32_bf16 v[112:115], v[172:175], v[188:191], v[112:115]
	v_mfma_f32_16x16x32_bf16 v[100:103], v[148:151], v[206:209], v[100:103]
	v_mfma_f32_16x16x32_bf16 v[96:99], v[172:175], v[206:209], v[96:99]
	v_mfma_f32_16x16x32_bf16 v[84:87], v[148:151], v[214:217], v[84:87]
	v_mfma_f32_16x16x32_bf16 v[80:83], v[172:175], v[214:217], v[80:83]
	s_setprio 0
	s_barrier
	s_add_i32 s59, s52, s40
	v_lshl_add_u64 v[198:199], s[30:31], 0, v[158:159]
	s_mov_b32 m0, s59
	ds_read_b128 v[176:179], v197 offset:16384
	ds_read_b128 v[180:183], v197 offset:17408
	ds_read_b128 v[184:187], v197 offset:18432
	ds_read_b128 v[188:191], v197 offset:19456
	ds_read_b128 v[202:205], v197 offset:20480
	ds_read_b128 v[206:209], v197 offset:21504
	ds_read_b128 v[210:213], v197 offset:22528
	ds_read_b128 v[214:217], v197 offset:23552
	global_load_lds_dwordx4 v[198:199], off
	s_add_i32 m0, s59, 0x2000
	s_add_u32 s60, s30, 0x40000
	v_lshl_add_u64 v[200:201], s[30:31], 0, v[162:163]
	s_addc_u32 s61, s31, 0
	s_add_i32 s59, s53, s40
	global_load_lds_dwordx4 v[200:201], off
	v_lshl_add_u64 v[218:219], s[60:61], 0, v[158:159]
	s_mov_b32 m0, s59
	v_lshl_add_u64 v[220:221], s[34:35], 0, v[160:161]
	global_load_lds_dwordx4 v[218:219], off
	v_lshl_add_u64 v[218:219], s[60:61], 0, v[162:163]
	s_add_i32 m0, s59, 0x2000
	s_nop 0
	global_load_lds_dwordx4 v[218:219], off
	v_lshl_add_u64 v[218:219], s[34:35], 0, v[156:157]
	s_mov_b32 m0, s41
	s_nop 0
	global_load_lds_dwordx4 v[218:219], off
	s_mov_b32 m0, s42
	s_nop 0
	global_load_lds_dwordx4 v[220:221], off
	s_waitcnt vmcnt(8)
	s_waitcnt lgkmcnt(0)
	s_barrier
	s_setprio 1
	s_waitcnt lgkmcnt(0)
	v_mfma_f32_16x16x32_bf16 v[72:75], v[60:63], v[176:179], v[72:75]
	v_mfma_f32_16x16x32_bf16 v[56:59], v[68:71], v[176:179], v[56:59]
	v_mfma_f32_16x16x32_bf16 v[44:47], v[60:63], v[184:187], v[44:47]
	v_mfma_f32_16x16x32_bf16 v[40:43], v[68:71], v[184:187], v[40:43]
	v_mfma_f32_16x16x32_bf16 v[28:31], v[60:63], v[202:205], v[28:31]
	v_mfma_f32_16x16x32_bf16 v[24:27], v[68:71], v[202:205], v[24:27]
	v_mfma_f32_16x16x32_bf16 v[12:15], v[60:63], v[210:213], v[12:15]
	v_mfma_f32_16x16x32_bf16 v[8:11], v[68:71], v[210:213], v[8:11]
	v_mfma_f32_16x16x32_bf16 v[72:75], v[64:67], v[180:183], v[72:75]
	v_mfma_f32_16x16x32_bf16 v[56:59], v[76:79], v[180:183], v[56:59]
	v_mfma_f32_16x16x32_bf16 v[44:47], v[64:67], v[188:191], v[44:47]
	v_mfma_f32_16x16x32_bf16 v[40:43], v[76:79], v[188:191], v[40:43]
	v_mfma_f32_16x16x32_bf16 v[28:31], v[64:67], v[206:209], v[28:31]
	v_mfma_f32_16x16x32_bf16 v[24:27], v[76:79], v[206:209], v[24:27]
	v_mfma_f32_16x16x32_bf16 v[12:15], v[64:67], v[214:217], v[12:15]
	v_mfma_f32_16x16x32_bf16 v[8:11], v[76:79], v[214:217], v[8:11]
	s_setprio 0
	s_setprio 1
	v_mfma_f32_16x16x32_bf16 v[52:55], v[144:147], v[176:179], v[52:55]
	v_mfma_f32_16x16x32_bf16 v[48:51], v[152:155], v[176:179], v[48:51]
	v_mfma_f32_16x16x32_bf16 v[36:39], v[144:147], v[184:187], v[36:39]
	v_mfma_f32_16x16x32_bf16 v[32:35], v[152:155], v[184:187], v[32:35]
	v_mfma_f32_16x16x32_bf16 v[20:23], v[144:147], v[202:205], v[20:23]
	v_mfma_f32_16x16x32_bf16 v[16:19], v[152:155], v[202:205], v[16:19]
	v_mfma_f32_16x16x32_bf16 v[4:7], v[144:147], v[210:213], v[4:7]
	v_mfma_f32_16x16x32_bf16 v[0:3], v[152:155], v[210:213], v[0:3]
	v_mfma_f32_16x16x32_bf16 v[52:55], v[148:151], v[180:183], v[52:55]
	v_mfma_f32_16x16x32_bf16 v[48:51], v[172:175], v[180:183], v[48:51]
	v_mfma_f32_16x16x32_bf16 v[36:39], v[148:151], v[188:191], v[36:39]
	v_mfma_f32_16x16x32_bf16 v[32:35], v[172:175], v[188:191], v[32:35]
	v_mfma_f32_16x16x32_bf16 v[20:23], v[148:151], v[206:209], v[20:23]
	v_mfma_f32_16x16x32_bf16 v[16:19], v[172:175], v[206:209], v[16:19]
	v_mfma_f32_16x16x32_bf16 v[4:7], v[148:151], v[214:217], v[4:7]
	v_mfma_f32_16x16x32_bf16 v[0:3], v[172:175], v[214:217], v[0:3]
	s_setprio 0
	s_barrier
	s_add_i32 s59, 0, 0x18000
	s_add_i32 s60, 0, 0x1c000
	v_add_u32_e32 v76, s59, v193
	v_add_u32_e32 v172, s60, v193
	ds_read_b128 v[60:63], v76
	ds_read_b128 v[64:67], v76 offset:1024
	ds_read_b128 v[68:71], v76 offset:2048
	ds_read_b128 v[76:79], v76 offset:3072
	ds_read_b128 v[144:147], v172
	ds_read_b128 v[148:151], v172 offset:1024
	ds_read_b128 v[152:155], v172 offset:2048
	ds_read_b128 v[172:175], v172 offset:3072
	s_add_u32 s34, s34, 0x40000
	s_addc_u32 s35, s35, 0
	s_mov_b32 m0, s43
	v_lshl_add_u64 v[222:223], s[34:35], 0, v[156:157]
	ds_read_b128 v[176:179], v197 offset:32768
	ds_read_b128 v[180:183], v197 offset:33792
	ds_read_b128 v[184:187], v197 offset:34816
	ds_read_b128 v[188:191], v197 offset:35840
	ds_read_b128 v[202:205], v197 offset:36864
	ds_read_b128 v[206:209], v197 offset:37888
	ds_read_b128 v[210:213], v197 offset:38912
	ds_read_b128 v[214:217], v197 offset:39936
	global_load_lds_dwordx4 v[222:223], off
	v_lshl_add_u64 v[222:223], s[34:35], 0, v[160:161]
	s_mov_b32 m0, s44
	s_nop 0
	global_load_lds_dwordx4 v[222:223], off
	s_waitcnt vmcnt(8)
	s_waitcnt lgkmcnt(0)
	s_barrier
	s_setprio 1
	s_waitcnt lgkmcnt(0)
	v_mfma_f32_16x16x32_bf16 v[140:143], v[60:63], v[176:179], v[140:143]
	v_mfma_f32_16x16x32_bf16 v[136:139], v[68:71], v[176:179], v[136:139]
	v_mfma_f32_16x16x32_bf16 v[124:127], v[60:63], v[184:187], v[124:127]
	v_mfma_f32_16x16x32_bf16 v[120:123], v[68:71], v[184:187], v[120:123]
	v_mfma_f32_16x16x32_bf16 v[108:111], v[60:63], v[202:205], v[108:111]
	v_mfma_f32_16x16x32_bf16 v[104:107], v[68:71], v[202:205], v[104:107]
	v_mfma_f32_16x16x32_bf16 v[92:95], v[60:63], v[210:213], v[92:95]
	v_mfma_f32_16x16x32_bf16 v[88:91], v[68:71], v[210:213], v[88:91]
	v_mfma_f32_16x16x32_bf16 v[140:143], v[64:67], v[180:183], v[140:143]
	v_mfma_f32_16x16x32_bf16 v[136:139], v[76:79], v[180:183], v[136:139]
	v_mfma_f32_16x16x32_bf16 v[124:127], v[64:67], v[188:191], v[124:127]
	v_mfma_f32_16x16x32_bf16 v[120:123], v[76:79], v[188:191], v[120:123]
	v_mfma_f32_16x16x32_bf16 v[108:111], v[64:67], v[206:209], v[108:111]
	v_mfma_f32_16x16x32_bf16 v[104:107], v[76:79], v[206:209], v[104:107]
	v_mfma_f32_16x16x32_bf16 v[92:95], v[64:67], v[214:217], v[92:95]
	v_mfma_f32_16x16x32_bf16 v[88:91], v[76:79], v[214:217], v[88:91]
	s_setprio 0
	s_setprio 1
	v_mfma_f32_16x16x32_bf16 v[132:135], v[144:147], v[176:179], v[132:135]
	v_mfma_f32_16x16x32_bf16 v[128:131], v[152:155], v[176:179], v[128:131]
	v_mfma_f32_16x16x32_bf16 v[116:119], v[144:147], v[184:187], v[116:119]
	v_mfma_f32_16x16x32_bf16 v[112:115], v[152:155], v[184:187], v[112:115]
	v_mfma_f32_16x16x32_bf16 v[100:103], v[144:147], v[202:205], v[100:103]
	v_mfma_f32_16x16x32_bf16 v[96:99], v[152:155], v[202:205], v[96:99]
	v_mfma_f32_16x16x32_bf16 v[84:87], v[144:147], v[210:213], v[84:87]
	v_mfma_f32_16x16x32_bf16 v[80:83], v[152:155], v[210:213], v[80:83]
	v_mfma_f32_16x16x32_bf16 v[132:135], v[148:151], v[180:183], v[132:135]
	v_mfma_f32_16x16x32_bf16 v[128:131], v[172:175], v[180:183], v[128:131]
	v_mfma_f32_16x16x32_bf16 v[116:119], v[148:151], v[188:191], v[116:119]
	v_mfma_f32_16x16x32_bf16 v[112:115], v[172:175], v[188:191], v[112:115]
	v_mfma_f32_16x16x32_bf16 v[100:103], v[148:151], v[206:209], v[100:103]
	v_mfma_f32_16x16x32_bf16 v[96:99], v[172:175], v[206:209], v[96:99]
	v_mfma_f32_16x16x32_bf16 v[84:87], v[148:151], v[214:217], v[84:87]
	v_mfma_f32_16x16x32_bf16 v[80:83], v[172:175], v[214:217], v[80:83]
	s_setprio 0
	s_barrier
	s_add_i32 s34, s59, s40
	v_lshl_add_u64 v[198:199], v[198:199], 0, s[8:9]
	s_mov_b32 m0, s34
	ds_read_b128 v[176:179], v197 offset:49152
	ds_read_b128 v[180:183], v197 offset:50176
	ds_read_b128 v[184:187], v197 offset:51200
	ds_read_b128 v[188:191], v197 offset:52224
	ds_read_b128 v[202:205], v197 offset:53248
	ds_read_b128 v[206:209], v197 offset:54272
	ds_read_b128 v[210:213], v197 offset:55296
	ds_read_b128 v[214:217], v197 offset:56320
	global_load_lds_dwordx4 v[198:199], off
	s_add_i32 m0, s34, 0x2000
	s_add_u32 s30, s30, 0x40080
	v_lshl_add_u64 v[198:199], v[200:201], 0, s[8:9]
	s_addc_u32 s31, s31, 0
	s_add_i32 s34, s60, s40
	global_load_lds_dwordx4 v[198:199], off
	v_lshl_add_u64 v[198:199], s[30:31], 0, v[158:159]
	s_mov_b32 m0, s34
	s_nop 0
	global_load_lds_dwordx4 v[198:199], off
	v_lshl_add_u64 v[198:199], s[30:31], 0, v[162:163]
	s_add_i32 m0, s34, 0x2000
	s_nop 0
	global_load_lds_dwordx4 v[198:199], off
	v_lshl_add_u64 v[198:199], v[218:219], 0, s[8:9]
	s_mov_b32 m0, s48
	s_nop 0
	global_load_lds_dwordx4 v[198:199], off
	v_lshl_add_u64 v[198:199], v[220:221], 0, s[8:9]
	s_mov_b32 m0, s49
	s_nop 0
	global_load_lds_dwordx4 v[198:199], off
	s_add_i32 s58, s58, 2
	s_add_u32 s28, s28, 0x100
	s_addc_u32 s29, s29, 0
	s_add_u32 s56, s56, 0x100
	s_addc_u32 s57, s57, 0
	s_cmp_gt_u32 s58, 13
	s_waitcnt vmcnt(8)
	s_waitcnt lgkmcnt(0)
	s_barrier
	s_setprio 1
	s_waitcnt lgkmcnt(0)
	v_mfma_f32_16x16x32_bf16 v[72:75], v[60:63], v[176:179], v[72:75]
	v_mfma_f32_16x16x32_bf16 v[56:59], v[68:71], v[176:179], v[56:59]
	v_mfma_f32_16x16x32_bf16 v[44:47], v[60:63], v[184:187], v[44:47]
	v_mfma_f32_16x16x32_bf16 v[40:43], v[68:71], v[184:187], v[40:43]
	v_mfma_f32_16x16x32_bf16 v[28:31], v[60:63], v[202:205], v[28:31]
	v_mfma_f32_16x16x32_bf16 v[24:27], v[68:71], v[202:205], v[24:27]
	v_mfma_f32_16x16x32_bf16 v[12:15], v[60:63], v[210:213], v[12:15]
	v_mfma_f32_16x16x32_bf16 v[8:11], v[68:71], v[210:213], v[8:11]
	v_mfma_f32_16x16x32_bf16 v[72:75], v[64:67], v[180:183], v[72:75]
	v_mfma_f32_16x16x32_bf16 v[56:59], v[76:79], v[180:183], v[56:59]
	v_mfma_f32_16x16x32_bf16 v[44:47], v[64:67], v[188:191], v[44:47]
	v_mfma_f32_16x16x32_bf16 v[40:43], v[76:79], v[188:191], v[40:43]
	v_mfma_f32_16x16x32_bf16 v[28:31], v[64:67], v[206:209], v[28:31]
	v_mfma_f32_16x16x32_bf16 v[24:27], v[76:79], v[206:209], v[24:27]
	v_mfma_f32_16x16x32_bf16 v[12:15], v[64:67], v[214:217], v[12:15]
	v_mfma_f32_16x16x32_bf16 v[8:11], v[76:79], v[214:217], v[8:11]
	s_setprio 0
	s_setprio 1
	v_mfma_f32_16x16x32_bf16 v[52:55], v[144:147], v[176:179], v[52:55]
	v_mfma_f32_16x16x32_bf16 v[48:51], v[152:155], v[176:179], v[48:51]
	v_mfma_f32_16x16x32_bf16 v[36:39], v[144:147], v[184:187], v[36:39]
	v_mfma_f32_16x16x32_bf16 v[32:35], v[152:155], v[184:187], v[32:35]
	v_mfma_f32_16x16x32_bf16 v[20:23], v[144:147], v[202:205], v[20:23]
	v_mfma_f32_16x16x32_bf16 v[16:19], v[152:155], v[202:205], v[16:19]
	v_mfma_f32_16x16x32_bf16 v[4:7], v[144:147], v[210:213], v[4:7]
	v_mfma_f32_16x16x32_bf16 v[0:3], v[152:155], v[210:213], v[0:3]
	v_mfma_f32_16x16x32_bf16 v[52:55], v[148:151], v[180:183], v[52:55]
	v_mfma_f32_16x16x32_bf16 v[48:51], v[172:175], v[180:183], v[48:51]
	v_mfma_f32_16x16x32_bf16 v[36:39], v[148:151], v[188:191], v[36:39]
	v_mfma_f32_16x16x32_bf16 v[32:35], v[172:175], v[188:191], v[32:35]
	v_mfma_f32_16x16x32_bf16 v[20:23], v[148:151], v[206:209], v[20:23]
	v_mfma_f32_16x16x32_bf16 v[16:19], v[172:175], v[206:209], v[16:19]
	v_mfma_f32_16x16x32_bf16 v[4:7], v[148:151], v[214:217], v[4:7]
	v_mfma_f32_16x16x32_bf16 v[0:3], v[172:175], v[214:217], v[0:3]
	s_setprio 0
	s_barrier
	s_cbranch_scc0 .LBB0_1077
	s_and_b64 vcc, exec, s[10:11]
	s_cbranch_vccz .LBB0_1080
	s_barrier

.LBB0_1156:
	ds_read_b128 v[128:131], v182
	ds_read_b128 v[132:135], v182 offset:1024
	ds_read_b128 v[136:139], v182 offset:2048
	ds_read_b128 v[140:143], v182 offset:3072
	ds_read_b128 v[176:179], v183
	ds_read_b128 v[186:189], v183 offset:1024
	ds_read_b128 v[190:193], v183 offset:2048
	ds_read_b128 v[194:197], v183 offset:3072
	s_add_u32 s22, s20, 0xfff80080
	s_addc_u32 s23, s21, -1
	s_cmp_eq_u32 s54, 28
	s_cselect_b32 s25, s13, s23
	s_cselect_b32 s24, s33, s22
	s_cselect_b32 s23, s11, s53
	s_cselect_b32 s22, s51, s52
	v_lshl_add_u64 v[198:199], s[20:21], 0, v[168:169]
	s_add_i32 m0, s36, 0xc000
	ds_read_b128 v[202:205], v184
	ds_read_b128 v[206:209], v184 offset:1024
	ds_read_b128 v[210:213], v184 offset:2048
	ds_read_b128 v[214:217], v184 offset:3072
	ds_read_b128 v[218:221], v184 offset:4096
	ds_read_b128 v[222:225], v184 offset:5120
	ds_read_b128 v[226:229], v184 offset:6144
	ds_read_b128 v[230:233], v184 offset:7168
	global_load_lds_dwordx4 v[198:199], off
	v_lshl_add_u64 v[198:199], s[20:21], 0, v[170:171]
	s_add_i32 m0, s36, 0xe000
	s_nop 0
	global_load_lds_dwordx4 v[198:199], off
	s_waitcnt vmcnt(8)
	s_waitcnt lgkmcnt(0)
	s_barrier
	s_setprio 1
	s_waitcnt lgkmcnt(0)
	v_mfma_f32_16x16x32_bf16 v[124:127], v[128:131], v[202:205], v[124:127]
	v_mfma_f32_16x16x32_bf16 v[120:123], v[136:139], v[202:205], v[120:123]
	v_mfma_f32_16x16x32_bf16 v[116:119], v[128:131], v[210:213], v[116:119]
	v_mfma_f32_16x16x32_bf16 v[112:115], v[136:139], v[210:213], v[112:115]
	v_mfma_f32_16x16x32_bf16 v[92:95], v[128:131], v[218:221], v[92:95]
	v_mfma_f32_16x16x32_bf16 v[88:91], v[136:139], v[218:221], v[88:91]
	v_mfma_f32_16x16x32_bf16 v[76:79], v[128:131], v[226:229], v[76:79]
	v_mfma_f32_16x16x32_bf16 v[72:75], v[136:139], v[226:229], v[72:75]
	v_mfma_f32_16x16x32_bf16 v[124:127], v[132:135], v[206:209], v[124:127]
	v_mfma_f32_16x16x32_bf16 v[120:123], v[140:143], v[206:209], v[120:123]
	v_mfma_f32_16x16x32_bf16 v[116:119], v[132:135], v[214:217], v[116:119]
	v_mfma_f32_16x16x32_bf16 v[112:115], v[140:143], v[214:217], v[112:115]
	v_mfma_f32_16x16x32_bf16 v[92:95], v[132:135], v[222:225], v[92:95]
	v_mfma_f32_16x16x32_bf16 v[88:91], v[140:143], v[222:225], v[88:91]
	v_mfma_f32_16x16x32_bf16 v[76:79], v[132:135], v[230:233], v[76:79]
	v_mfma_f32_16x16x32_bf16 v[72:75], v[140:143], v[230:233], v[72:75]
	s_setprio 0
	s_setprio 1
	v_mfma_f32_16x16x32_bf16 v[108:111], v[176:179], v[202:205], v[108:111]
	v_mfma_f32_16x16x32_bf16 v[104:107], v[190:193], v[202:205], v[104:107]
	v_mfma_f32_16x16x32_bf16 v[100:103], v[176:179], v[210:213], v[100:103]
	v_mfma_f32_16x16x32_bf16 v[96:99], v[190:193], v[210:213], v[96:99]
	v_mfma_f32_16x16x32_bf16 v[84:87], v[176:179], v[218:221], v[84:87]
	v_mfma_f32_16x16x32_bf16 v[80:83], v[190:193], v[218:221], v[80:83]
	v_mfma_f32_16x16x32_bf16 v[68:71], v[176:179], v[226:229], v[68:71]
	v_mfma_f32_16x16x32_bf16 v[64:67], v[190:193], v[226:229], v[64:67]
	v_mfma_f32_16x16x32_bf16 v[108:111], v[186:189], v[206:209], v[108:111]
	v_mfma_f32_16x16x32_bf16 v[104:107], v[194:197], v[206:209], v[104:107]
	v_mfma_f32_16x16x32_bf16 v[100:103], v[186:189], v[214:217], v[100:103]
	v_mfma_f32_16x16x32_bf16 v[96:99], v[194:197], v[214:217], v[96:99]
	v_mfma_f32_16x16x32_bf16 v[84:87], v[186:189], v[222:225], v[84:87]
	v_mfma_f32_16x16x32_bf16 v[80:83], v[194:197], v[222:225], v[80:83]
	v_mfma_f32_16x16x32_bf16 v[68:71], v[186:189], v[230:233], v[68:71]
	v_mfma_f32_16x16x32_bf16 v[64:67], v[194:197], v[230:233], v[64:67]
	s_setprio 0
	s_barrier
	s_add_i32 s55, s49, s35
	v_lshl_add_u64 v[198:199], s[22:23], 0, v[146:147]
	s_mov_b32 m0, s55
	ds_read_b128 v[202:205], v184 offset:16384
	ds_read_b128 v[206:209], v184 offset:17408
	ds_read_b128 v[210:213], v184 offset:18432
	ds_read_b128 v[214:217], v184 offset:19456
	ds_read_b128 v[218:221], v184 offset:20480
	ds_read_b128 v[222:225], v184 offset:21504
	ds_read_b128 v[226:229], v184 offset:22528
	ds_read_b128 v[230:233], v184 offset:23552
	global_load_lds_dwordx4 v[198:199], off
	s_add_i32 m0, s55, 0x2000
	s_add_u32 s56, s22, 0x80000
	v_lshl_add_u64 v[200:201], s[22:23], 0, v[150:151]
	s_addc_u32 s57, s23, 0
	s_add_i32 s55, s50, s35
	global_load_lds_dwordx4 v[200:201], off
	v_lshl_add_u64 v[234:235], s[56:57], 0, v[146:147]
	s_mov_b32 m0, s55
	v_lshl_add_u64 v[236:237], s[24:25], 0, v[148:149]
	global_load_lds_dwordx4 v[234:235], off
	v_lshl_add_u64 v[234:235], s[56:57], 0, v[150:151]
	s_add_i32 m0, s55, 0x2000
	s_nop 0
	global_load_lds_dwordx4 v[234:235], off
	v_lshl_add_u64 v[234:235], s[24:25], 0, v[144:145]
	s_mov_b32 m0, s36
	s_nop 0
	global_load_lds_dwordx4 v[234:235], off
	s_mov_b32 m0, s37
	s_nop 0
	global_load_lds_dwordx4 v[236:237], off
	s_waitcnt vmcnt(8)
	s_waitcnt lgkmcnt(0)
	s_barrier
	s_setprio 1
	s_waitcnt lgkmcnt(0)
	v_mfma_f32_16x16x32_bf16 v[60:63], v[128:131], v[202:205], v[60:63]
	v_mfma_f32_16x16x32_bf16 v[56:59], v[136:139], v[202:205], v[56:59]
	v_mfma_f32_16x16x32_bf16 v[44:47], v[128:131], v[210:213], v[44:47]
	v_mfma_f32_16x16x32_bf16 v[40:43], v[136:139], v[210:213], v[40:43]
	v_mfma_f32_16x16x32_bf16 v[28:31], v[128:131], v[218:221], v[28:31]
	v_mfma_f32_16x16x32_bf16 v[24:27], v[136:139], v[218:221], v[24:27]
	v_mfma_f32_16x16x32_bf16 v[12:15], v[128:131], v[226:229], v[12:15]
	v_mfma_f32_16x16x32_bf16 v[8:11], v[136:139], v[226:229], v[8:11]
	v_mfma_f32_16x16x32_bf16 v[60:63], v[132:135], v[206:209], v[60:63]
	v_mfma_f32_16x16x32_bf16 v[56:59], v[140:143], v[206:209], v[56:59]
	v_mfma_f32_16x16x32_bf16 v[44:47], v[132:135], v[214:217], v[44:47]
	v_mfma_f32_16x16x32_bf16 v[40:43], v[140:143], v[214:217], v[40:43]
	v_mfma_f32_16x16x32_bf16 v[28:31], v[132:135], v[222:225], v[28:31]
	v_mfma_f32_16x16x32_bf16 v[24:27], v[140:143], v[222:225], v[24:27]
	v_mfma_f32_16x16x32_bf16 v[12:15], v[132:135], v[230:233], v[12:15]
	v_mfma_f32_16x16x32_bf16 v[8:11], v[140:143], v[230:233], v[8:11]
	s_setprio 0
	s_setprio 1
	v_mfma_f32_16x16x32_bf16 v[52:55], v[176:179], v[202:205], v[52:55]
	v_mfma_f32_16x16x32_bf16 v[48:51], v[190:193], v[202:205], v[48:51]
	v_mfma_f32_16x16x32_bf16 v[36:39], v[176:179], v[210:213], v[36:39]
	v_mfma_f32_16x16x32_bf16 v[32:35], v[190:193], v[210:213], v[32:35]
	v_mfma_f32_16x16x32_bf16 v[20:23], v[176:179], v[218:221], v[20:23]
	v_mfma_f32_16x16x32_bf16 v[16:19], v[190:193], v[218:221], v[16:19]
	v_mfma_f32_16x16x32_bf16 v[4:7], v[176:179], v[226:229], v[4:7]
	v_mfma_f32_16x16x32_bf16 v[0:3], v[190:193], v[226:229], v[0:3]
	v_mfma_f32_16x16x32_bf16 v[52:55], v[186:189], v[206:209], v[52:55]
	v_mfma_f32_16x16x32_bf16 v[48:51], v[194:197], v[206:209], v[48:51]
	v_mfma_f32_16x16x32_bf16 v[36:39], v[186:189], v[214:217], v[36:39]
	v_mfma_f32_16x16x32_bf16 v[32:35], v[194:197], v[214:217], v[32:35]
	v_mfma_f32_16x16x32_bf16 v[20:23], v[186:189], v[222:225], v[20:23]
	v_mfma_f32_16x16x32_bf16 v[16:19], v[194:197], v[222:225], v[16:19]
	v_mfma_f32_16x16x32_bf16 v[4:7], v[186:189], v[230:233], v[4:7]
	v_mfma_f32_16x16x32_bf16 v[0:3], v[194:197], v[230:233], v[0:3]
	s_setprio 0
	s_barrier
	s_add_i32 s55, 0, 0x18000
	s_add_i32 s56, 0, 0x1c000
	v_add_u32_e32 v140, s55, v180
	v_add_u32_e32 v185, s56, v180
	ds_read_b128 v[128:131], v140
	ds_read_b128 v[132:135], v140 offset:1024
	ds_read_b128 v[136:139], v140 offset:2048
	ds_read_b128 v[140:143], v140 offset:3072
	ds_read_b128 v[176:179], v185
	ds_read_b128 v[186:189], v185 offset:1024
	ds_read_b128 v[190:193], v185 offset:2048
	ds_read_b128 v[194:197], v185 offset:3072
	s_add_u32 s24, s24, 0x80000
	s_addc_u32 s25, s25, 0
	s_mov_b32 m0, s38
	v_lshl_add_u64 v[238:239], s[24:25], 0, v[144:145]
	ds_read_b128 v[202:205], v184 offset:32768
	ds_read_b128 v[206:209], v184 offset:33792
	ds_read_b128 v[210:213], v184 offset:34816
	ds_read_b128 v[214:217], v184 offset:35840
	ds_read_b128 v[218:221], v184 offset:36864
	ds_read_b128 v[222:225], v184 offset:37888
	ds_read_b128 v[226:229], v184 offset:38912
	ds_read_b128 v[230:233], v184 offset:39936
	global_load_lds_dwordx4 v[238:239], off
	v_lshl_add_u64 v[238:239], s[24:25], 0, v[148:149]
	s_mov_b32 m0, s39
	s_nop 0
	global_load_lds_dwordx4 v[238:239], off
	s_waitcnt vmcnt(8)
	s_waitcnt lgkmcnt(0)
	s_barrier
	s_setprio 1
	s_waitcnt lgkmcnt(0)
	v_mfma_f32_16x16x32_bf16 v[124:127], v[128:131], v[202:205], v[124:127]
	v_mfma_f32_16x16x32_bf16 v[120:123], v[136:139], v[202:205], v[120:123]
	v_mfma_f32_16x16x32_bf16 v[116:119], v[128:131], v[210:213], v[116:119]
	v_mfma_f32_16x16x32_bf16 v[112:115], v[136:139], v[210:213], v[112:115]
	v_mfma_f32_16x16x32_bf16 v[92:95], v[128:131], v[218:221], v[92:95]
	v_mfma_f32_16x16x32_bf16 v[88:91], v[136:139], v[218:221], v[88:91]
	v_mfma_f32_16x16x32_bf16 v[76:79], v[128:131], v[226:229], v[76:79]
	v_mfma_f32_16x16x32_bf16 v[72:75], v[136:139], v[226:229], v[72:75]
	v_mfma_f32_16x16x32_bf16 v[124:127], v[132:135], v[206:209], v[124:127]
	v_mfma_f32_16x16x32_bf16 v[120:123], v[140:143], v[206:209], v[120:123]
	v_mfma_f32_16x16x32_bf16 v[116:119], v[132:135], v[214:217], v[116:119]
	v_mfma_f32_16x16x32_bf16 v[112:115], v[140:143], v[214:217], v[112:115]
	v_mfma_f32_16x16x32_bf16 v[92:95], v[132:135], v[222:225], v[92:95]
	v_mfma_f32_16x16x32_bf16 v[88:91], v[140:143], v[222:225], v[88:91]
	v_mfma_f32_16x16x32_bf16 v[76:79], v[132:135], v[230:233], v[76:79]
	v_mfma_f32_16x16x32_bf16 v[72:75], v[140:143], v[230:233], v[72:75]
	s_setprio 0
	s_setprio 1
	v_mfma_f32_16x16x32_bf16 v[108:111], v[176:179], v[202:205], v[108:111]
	v_mfma_f32_16x16x32_bf16 v[104:107], v[190:193], v[202:205], v[104:107]
	v_mfma_f32_16x16x32_bf16 v[100:103], v[176:179], v[210:213], v[100:103]
	v_mfma_f32_16x16x32_bf16 v[96:99], v[190:193], v[210:213], v[96:99]
	v_mfma_f32_16x16x32_bf16 v[84:87], v[176:179], v[218:221], v[84:87]
	v_mfma_f32_16x16x32_bf16 v[80:83], v[190:193], v[218:221], v[80:83]
	v_mfma_f32_16x16x32_bf16 v[68:71], v[176:179], v[226:229], v[68:71]
	v_mfma_f32_16x16x32_bf16 v[64:67], v[190:193], v[226:229], v[64:67]
	v_mfma_f32_16x16x32_bf16 v[108:111], v[186:189], v[206:209], v[108:111]
	v_mfma_f32_16x16x32_bf16 v[104:107], v[194:197], v[206:209], v[104:107]
	v_mfma_f32_16x16x32_bf16 v[100:103], v[186:189], v[214:217], v[100:103]
	v_mfma_f32_16x16x32_bf16 v[96:99], v[194:197], v[214:217], v[96:99]
	v_mfma_f32_16x16x32_bf16 v[84:87], v[186:189], v[222:225], v[84:87]
	v_mfma_f32_16x16x32_bf16 v[80:83], v[194:197], v[222:225], v[80:83]
	v_mfma_f32_16x16x32_bf16 v[68:71], v[186:189], v[230:233], v[68:71]
	v_mfma_f32_16x16x32_bf16 v[64:67], v[194:197], v[230:233], v[64:67]
	s_setprio 0
	s_barrier
	s_add_i32 s24, s55, s35
	v_lshl_add_u64 v[198:199], v[198:199], 0, s[6:7]
	s_mov_b32 m0, s24
	ds_read_b128 v[202:205], v184 offset:49152
	ds_read_b128 v[206:209], v184 offset:50176
	ds_read_b128 v[210:213], v184 offset:51200
	ds_read_b128 v[214:217], v184 offset:52224
	ds_read_b128 v[218:221], v184 offset:53248
	ds_read_b128 v[222:225], v184 offset:54272
	ds_read_b128 v[226:229], v184 offset:55296
	ds_read_b128 v[230:233], v184 offset:56320
	global_load_lds_dwordx4 v[198:199], off
	s_add_i32 m0, s24, 0x2000
	s_add_u32 s22, s22, 0x80080
	v_lshl_add_u64 v[198:199], v[200:201], 0, s[6:7]
	s_addc_u32 s23, s23, 0
	s_add_i32 s24, s56, s35
	global_load_lds_dwordx4 v[198:199], off
	v_lshl_add_u64 v[198:199], s[22:23], 0, v[146:147]
	s_mov_b32 m0, s24
	s_nop 0
	global_load_lds_dwordx4 v[198:199], off
	v_lshl_add_u64 v[198:199], s[22:23], 0, v[150:151]
	s_add_i32 m0, s24, 0x2000
	s_nop 0
	global_load_lds_dwordx4 v[198:199], off
	v_lshl_add_u64 v[198:199], v[234:235], 0, s[6:7]
	s_mov_b32 m0, s45
	s_nop 0
	global_load_lds_dwordx4 v[198:199], off
	v_lshl_add_u64 v[198:199], v[236:237], 0, s[6:7]
	s_mov_b32 m0, s46
	s_nop 0
	global_load_lds_dwordx4 v[198:199], off
	s_add_i32 s54, s54, 2
	s_add_u32 s20, s20, 0x100
	s_addc_u32 s21, s21, 0
	s_add_u32 s52, s52, 0x100
	s_addc_u32 s53, s53, 0
	s_cmp_gt_u32 s54, 29
	s_waitcnt vmcnt(8)
	s_waitcnt lgkmcnt(0)
	s_barrier
	s_setprio 1
	s_waitcnt lgkmcnt(0)
	v_mfma_f32_16x16x32_bf16 v[60:63], v[128:131], v[202:205], v[60:63]
	v_mfma_f32_16x16x32_bf16 v[56:59], v[136:139], v[202:205], v[56:59]
	v_mfma_f32_16x16x32_bf16 v[44:47], v[128:131], v[210:213], v[44:47]
	v_mfma_f32_16x16x32_bf16 v[40:43], v[136:139], v[210:213], v[40:43]
	v_mfma_f32_16x16x32_bf16 v[28:31], v[128:131], v[218:221], v[28:31]
	v_mfma_f32_16x16x32_bf16 v[24:27], v[136:139], v[218:221], v[24:27]
	v_mfma_f32_16x16x32_bf16 v[12:15], v[128:131], v[226:229], v[12:15]
	v_mfma_f32_16x16x32_bf16 v[8:11], v[136:139], v[226:229], v[8:11]
	v_mfma_f32_16x16x32_bf16 v[60:63], v[132:135], v[206:209], v[60:63]
	v_mfma_f32_16x16x32_bf16 v[56:59], v[140:143], v[206:209], v[56:59]
	v_mfma_f32_16x16x32_bf16 v[44:47], v[132:135], v[214:217], v[44:47]
	v_mfma_f32_16x16x32_bf16 v[40:43], v[140:143], v[214:217], v[40:43]
	v_mfma_f32_16x16x32_bf16 v[28:31], v[132:135], v[222:225], v[28:31]
	v_mfma_f32_16x16x32_bf16 v[24:27], v[140:143], v[222:225], v[24:27]
	v_mfma_f32_16x16x32_bf16 v[12:15], v[132:135], v[230:233], v[12:15]
	v_mfma_f32_16x16x32_bf16 v[8:11], v[140:143], v[230:233], v[8:11]
	s_setprio 0
	s_setprio 1
	v_mfma_f32_16x16x32_bf16 v[52:55], v[176:179], v[202:205], v[52:55]
	v_mfma_f32_16x16x32_bf16 v[48:51], v[190:193], v[202:205], v[48:51]
	v_mfma_f32_16x16x32_bf16 v[36:39], v[176:179], v[210:213], v[36:39]
	v_mfma_f32_16x16x32_bf16 v[32:35], v[190:193], v[210:213], v[32:35]
	v_mfma_f32_16x16x32_bf16 v[20:23], v[176:179], v[218:221], v[20:23]
	v_mfma_f32_16x16x32_bf16 v[16:19], v[190:193], v[218:221], v[16:19]
	v_mfma_f32_16x16x32_bf16 v[4:7], v[176:179], v[226:229], v[4:7]
	v_mfma_f32_16x16x32_bf16 v[0:3], v[190:193], v[226:229], v[0:3]
	v_mfma_f32_16x16x32_bf16 v[52:55], v[186:189], v[206:209], v[52:55]
	v_mfma_f32_16x16x32_bf16 v[48:51], v[194:197], v[206:209], v[48:51]
	v_mfma_f32_16x16x32_bf16 v[36:39], v[186:189], v[214:217], v[36:39]
	v_mfma_f32_16x16x32_bf16 v[32:35], v[194:197], v[214:217], v[32:35]
	v_mfma_f32_16x16x32_bf16 v[20:23], v[186:189], v[222:225], v[20:23]
	v_mfma_f32_16x16x32_bf16 v[16:19], v[194:197], v[222:225], v[16:19]
	v_mfma_f32_16x16x32_bf16 v[4:7], v[186:189], v[230:233], v[4:7]
	v_mfma_f32_16x16x32_bf16 v[0:3], v[194:197], v[230:233], v[0:3]
	s_setprio 0
	s_barrier
	s_cbranch_scc0 .LBB0_1156
	s_and_b64 vcc, exec, s[8:9]
	s_cbranch_vccz .LBB0_1159
	s_barrier

.LBB0_1308:
	ds_read_b128 v[150:153], v147
	ds_read_b128 v[154:157], v147 offset:1024
	ds_read_b128 v[158:161], v147 offset:2048
	ds_read_b128 v[162:165], v147 offset:3072
	ds_read_b128 v[166:169], v148
	ds_read_b128 v[170:173], v148 offset:1024
	ds_read_b128 v[174:177], v148 offset:2048
	ds_read_b128 v[178:181], v148 offset:3072
	s_add_u32 s24, s22, 0xfffc0080
	s_addc_u32 s25, s23, -1
	s_cmp_eq_u32 s54, 12
	s_cselect_b32 s29, s15, s25
	s_cselect_b32 s28, s50, s24
	s_cselect_b32 s25, s13, s53
	s_cselect_b32 s24, s51, s52
	v_lshl_add_u64 v[198:199], s[22:23], 0, v[136:137]
	s_add_i32 m0, s21, 0xc000
	ds_read_b128 v[182:185], v149
	ds_read_b128 v[186:189], v149 offset:1024
	ds_read_b128 v[190:193], v149 offset:2048
	ds_read_b128 v[194:197], v149 offset:3072
	ds_read_b128 v[202:205], v149 offset:4096
	ds_read_b128 v[206:209], v149 offset:5120
	ds_read_b128 v[210:213], v149 offset:6144
	ds_read_b128 v[214:217], v149 offset:7168
	global_load_lds_dwordx4 v[198:199], off
	v_lshl_add_u64 v[198:199], s[22:23], 0, v[138:139]
	s_add_i32 m0, s21, 0xe000
	s_nop 0
	global_load_lds_dwordx4 v[198:199], off
	s_waitcnt vmcnt(8)
	s_waitcnt lgkmcnt(0)
	s_barrier
	s_setprio 1
	s_waitcnt lgkmcnt(0)
	v_mfma_f32_16x16x32_bf16 v[124:127], v[150:153], v[182:185], v[124:127]
	v_mfma_f32_16x16x32_bf16 v[116:119], v[158:161], v[182:185], v[116:119]
	v_mfma_f32_16x16x32_bf16 v[108:111], v[150:153], v[190:193], v[108:111]
	v_mfma_f32_16x16x32_bf16 v[100:103], v[158:161], v[190:193], v[100:103]
	v_mfma_f32_16x16x32_bf16 v[92:95], v[150:153], v[202:205], v[92:95]
	v_mfma_f32_16x16x32_bf16 v[84:87], v[158:161], v[202:205], v[84:87]
	v_mfma_f32_16x16x32_bf16 v[76:79], v[150:153], v[210:213], v[76:79]
	v_mfma_f32_16x16x32_bf16 v[68:71], v[158:161], v[210:213], v[68:71]
	v_mfma_f32_16x16x32_bf16 v[124:127], v[154:157], v[186:189], v[124:127]
	v_mfma_f32_16x16x32_bf16 v[116:119], v[162:165], v[186:189], v[116:119]
	v_mfma_f32_16x16x32_bf16 v[108:111], v[154:157], v[194:197], v[108:111]
	v_mfma_f32_16x16x32_bf16 v[100:103], v[162:165], v[194:197], v[100:103]
	v_mfma_f32_16x16x32_bf16 v[92:95], v[154:157], v[206:209], v[92:95]
	v_mfma_f32_16x16x32_bf16 v[84:87], v[162:165], v[206:209], v[84:87]
	v_mfma_f32_16x16x32_bf16 v[76:79], v[154:157], v[214:217], v[76:79]
	v_mfma_f32_16x16x32_bf16 v[68:71], v[162:165], v[214:217], v[68:71]
	s_setprio 0
	s_setprio 1
	v_mfma_f32_16x16x32_bf16 v[120:123], v[166:169], v[182:185], v[120:123]
	v_mfma_f32_16x16x32_bf16 v[112:115], v[174:177], v[182:185], v[112:115]
	v_mfma_f32_16x16x32_bf16 v[104:107], v[166:169], v[190:193], v[104:107]
	v_mfma_f32_16x16x32_bf16 v[96:99], v[174:177], v[190:193], v[96:99]
	v_mfma_f32_16x16x32_bf16 v[88:91], v[166:169], v[202:205], v[88:91]
	v_mfma_f32_16x16x32_bf16 v[80:83], v[174:177], v[202:205], v[80:83]
	v_mfma_f32_16x16x32_bf16 v[72:75], v[166:169], v[210:213], v[72:75]
	v_mfma_f32_16x16x32_bf16 v[64:67], v[174:177], v[210:213], v[64:67]
	v_mfma_f32_16x16x32_bf16 v[120:123], v[170:173], v[186:189], v[120:123]
	v_mfma_f32_16x16x32_bf16 v[112:115], v[178:181], v[186:189], v[112:115]
	v_mfma_f32_16x16x32_bf16 v[104:107], v[170:173], v[194:197], v[104:107]
	v_mfma_f32_16x16x32_bf16 v[96:99], v[178:181], v[194:197], v[96:99]
	v_mfma_f32_16x16x32_bf16 v[88:91], v[170:173], v[206:209], v[88:91]
	v_mfma_f32_16x16x32_bf16 v[80:83], v[178:181], v[206:209], v[80:83]
	v_mfma_f32_16x16x32_bf16 v[72:75], v[170:173], v[214:217], v[72:75]
	v_mfma_f32_16x16x32_bf16 v[64:67], v[178:181], v[214:217], v[64:67]
	s_setprio 0
	s_barrier
	s_add_i32 s55, s47, s36
	v_lshl_add_u64 v[198:199], s[24:25], 0, v[132:133]
	s_mov_b32 m0, s55
	ds_read_b128 v[182:185], v149 offset:16384
	ds_read_b128 v[186:189], v149 offset:17408
	ds_read_b128 v[190:193], v149 offset:18432
	ds_read_b128 v[194:197], v149 offset:19456
	ds_read_b128 v[202:205], v149 offset:20480
	ds_read_b128 v[206:209], v149 offset:21504
	ds_read_b128 v[210:213], v149 offset:22528
	ds_read_b128 v[214:217], v149 offset:23552
	global_load_lds_dwordx4 v[198:199], off
	s_add_i32 m0, s55, 0x2000
	s_add_u32 s56, s24, 0x40000
	v_lshl_add_u64 v[200:201], s[24:25], 0, v[128:129]
	s_addc_u32 s57, s25, 0
	s_add_i32 s55, s48, s36
	global_load_lds_dwordx4 v[200:201], off
	v_lshl_add_u64 v[218:219], s[56:57], 0, v[132:133]
	s_mov_b32 m0, s55
	v_lshl_add_u64 v[220:221], s[28:29], 0, v[130:131]
	global_load_lds_dwordx4 v[218:219], off
	v_lshl_add_u64 v[218:219], s[56:57], 0, v[128:129]
	s_add_i32 m0, s55, 0x2000
	s_nop 0
	global_load_lds_dwordx4 v[218:219], off
	v_lshl_add_u64 v[218:219], s[28:29], 0, v[134:135]
	s_mov_b32 m0, s21
	s_nop 0
	global_load_lds_dwordx4 v[218:219], off
	s_mov_b32 m0, s39
	s_nop 0
	global_load_lds_dwordx4 v[220:221], off
	s_waitcnt vmcnt(8)
	s_waitcnt lgkmcnt(0)
	s_barrier
	s_setprio 1
	s_waitcnt lgkmcnt(0)
	v_mfma_f32_16x16x32_bf16 v[60:63], v[150:153], v[182:185], v[60:63]
	v_mfma_f32_16x16x32_bf16 v[52:55], v[158:161], v[182:185], v[52:55]
	v_mfma_f32_16x16x32_bf16 v[44:47], v[150:153], v[190:193], v[44:47]
	v_mfma_f32_16x16x32_bf16 v[36:39], v[158:161], v[190:193], v[36:39]
	v_mfma_f32_16x16x32_bf16 v[28:31], v[150:153], v[202:205], v[28:31]
	v_mfma_f32_16x16x32_bf16 v[20:23], v[158:161], v[202:205], v[20:23]
	v_mfma_f32_16x16x32_bf16 v[12:15], v[150:153], v[210:213], v[12:15]
	v_mfma_f32_16x16x32_bf16 v[4:7], v[158:161], v[210:213], v[4:7]
	v_mfma_f32_16x16x32_bf16 v[60:63], v[154:157], v[186:189], v[60:63]
	v_mfma_f32_16x16x32_bf16 v[52:55], v[162:165], v[186:189], v[52:55]
	v_mfma_f32_16x16x32_bf16 v[44:47], v[154:157], v[194:197], v[44:47]
	v_mfma_f32_16x16x32_bf16 v[36:39], v[162:165], v[194:197], v[36:39]
	v_mfma_f32_16x16x32_bf16 v[28:31], v[154:157], v[206:209], v[28:31]
	v_mfma_f32_16x16x32_bf16 v[20:23], v[162:165], v[206:209], v[20:23]
	v_mfma_f32_16x16x32_bf16 v[12:15], v[154:157], v[214:217], v[12:15]
	v_mfma_f32_16x16x32_bf16 v[4:7], v[162:165], v[214:217], v[4:7]
	s_setprio 0
	s_setprio 1
	v_mfma_f32_16x16x32_bf16 v[56:59], v[166:169], v[182:185], v[56:59]
	v_mfma_f32_16x16x32_bf16 v[48:51], v[174:177], v[182:185], v[48:51]
	v_mfma_f32_16x16x32_bf16 v[40:43], v[166:169], v[190:193], v[40:43]
	v_mfma_f32_16x16x32_bf16 v[32:35], v[174:177], v[190:193], v[32:35]
	v_mfma_f32_16x16x32_bf16 v[24:27], v[166:169], v[202:205], v[24:27]
	v_mfma_f32_16x16x32_bf16 v[16:19], v[174:177], v[202:205], v[16:19]
	v_mfma_f32_16x16x32_bf16 v[8:11], v[166:169], v[210:213], v[8:11]
	v_mfma_f32_16x16x32_bf16 v[0:3], v[174:177], v[210:213], v[0:3]
	v_mfma_f32_16x16x32_bf16 v[56:59], v[170:173], v[186:189], v[56:59]
	v_mfma_f32_16x16x32_bf16 v[48:51], v[178:181], v[186:189], v[48:51]
	v_mfma_f32_16x16x32_bf16 v[40:43], v[170:173], v[194:197], v[40:43]
	v_mfma_f32_16x16x32_bf16 v[32:35], v[178:181], v[194:197], v[32:35]
	v_mfma_f32_16x16x32_bf16 v[24:27], v[170:173], v[206:209], v[24:27]
	v_mfma_f32_16x16x32_bf16 v[16:19], v[178:181], v[206:209], v[16:19]
	v_mfma_f32_16x16x32_bf16 v[8:11], v[170:173], v[214:217], v[8:11]
	v_mfma_f32_16x16x32_bf16 v[0:3], v[178:181], v[214:217], v[0:3]
	s_setprio 0
	s_barrier
	s_add_i32 s55, 0, 0x18000
	s_add_i32 s56, 0, 0x1c000
	v_add_u32_e32 v162, s55, v145
	v_add_u32_e32 v178, s56, v145
	ds_read_b128 v[150:153], v162
	ds_read_b128 v[154:157], v162 offset:1024
	ds_read_b128 v[158:161], v162 offset:2048
	ds_read_b128 v[162:165], v162 offset:3072
	ds_read_b128 v[166:169], v178
	ds_read_b128 v[170:173], v178 offset:1024
	ds_read_b128 v[174:177], v178 offset:2048
	ds_read_b128 v[178:181], v178 offset:3072
	s_add_u32 s28, s28, 0x40000
	s_addc_u32 s29, s29, 0
	s_mov_b32 m0, s40
	v_lshl_add_u64 v[222:223], s[28:29], 0, v[134:135]
	ds_read_b128 v[182:185], v149 offset:32768
	ds_read_b128 v[186:189], v149 offset:33792
	ds_read_b128 v[190:193], v149 offset:34816
	ds_read_b128 v[194:197], v149 offset:35840
	ds_read_b128 v[202:205], v149 offset:36864
	ds_read_b128 v[206:209], v149 offset:37888
	ds_read_b128 v[210:213], v149 offset:38912
	ds_read_b128 v[214:217], v149 offset:39936
	global_load_lds_dwordx4 v[222:223], off
	v_lshl_add_u64 v[222:223], s[28:29], 0, v[130:131]
	s_mov_b32 m0, s41
	s_nop 0
	global_load_lds_dwordx4 v[222:223], off
	s_waitcnt vmcnt(8)
	s_waitcnt lgkmcnt(0)
	s_barrier
	s_setprio 1
	s_waitcnt lgkmcnt(0)
	v_mfma_f32_16x16x32_bf16 v[124:127], v[150:153], v[182:185], v[124:127]
	v_mfma_f32_16x16x32_bf16 v[116:119], v[158:161], v[182:185], v[116:119]
	v_mfma_f32_16x16x32_bf16 v[108:111], v[150:153], v[190:193], v[108:111]
	v_mfma_f32_16x16x32_bf16 v[100:103], v[158:161], v[190:193], v[100:103]
	v_mfma_f32_16x16x32_bf16 v[92:95], v[150:153], v[202:205], v[92:95]
	v_mfma_f32_16x16x32_bf16 v[84:87], v[158:161], v[202:205], v[84:87]
	v_mfma_f32_16x16x32_bf16 v[76:79], v[150:153], v[210:213], v[76:79]
	v_mfma_f32_16x16x32_bf16 v[68:71], v[158:161], v[210:213], v[68:71]
	v_mfma_f32_16x16x32_bf16 v[124:127], v[154:157], v[186:189], v[124:127]
	v_mfma_f32_16x16x32_bf16 v[116:119], v[162:165], v[186:189], v[116:119]
	v_mfma_f32_16x16x32_bf16 v[108:111], v[154:157], v[194:197], v[108:111]
	v_mfma_f32_16x16x32_bf16 v[100:103], v[162:165], v[194:197], v[100:103]
	v_mfma_f32_16x16x32_bf16 v[92:95], v[154:157], v[206:209], v[92:95]
	v_mfma_f32_16x16x32_bf16 v[84:87], v[162:165], v[206:209], v[84:87]
	v_mfma_f32_16x16x32_bf16 v[76:79], v[154:157], v[214:217], v[76:79]
	v_mfma_f32_16x16x32_bf16 v[68:71], v[162:165], v[214:217], v[68:71]
	s_setprio 0
	s_setprio 1
	v_mfma_f32_16x16x32_bf16 v[120:123], v[166:169], v[182:185], v[120:123]
	v_mfma_f32_16x16x32_bf16 v[112:115], v[174:177], v[182:185], v[112:115]
	v_mfma_f32_16x16x32_bf16 v[104:107], v[166:169], v[190:193], v[104:107]
	v_mfma_f32_16x16x32_bf16 v[96:99], v[174:177], v[190:193], v[96:99]
	v_mfma_f32_16x16x32_bf16 v[88:91], v[166:169], v[202:205], v[88:91]
	v_mfma_f32_16x16x32_bf16 v[80:83], v[174:177], v[202:205], v[80:83]
	v_mfma_f32_16x16x32_bf16 v[72:75], v[166:169], v[210:213], v[72:75]
	v_mfma_f32_16x16x32_bf16 v[64:67], v[174:177], v[210:213], v[64:67]
	v_mfma_f32_16x16x32_bf16 v[120:123], v[170:173], v[186:189], v[120:123]
	v_mfma_f32_16x16x32_bf16 v[112:115], v[178:181], v[186:189], v[112:115]
	v_mfma_f32_16x16x32_bf16 v[104:107], v[170:173], v[194:197], v[104:107]
	v_mfma_f32_16x16x32_bf16 v[96:99], v[178:181], v[194:197], v[96:99]
	v_mfma_f32_16x16x32_bf16 v[88:91], v[170:173], v[206:209], v[88:91]
	v_mfma_f32_16x16x32_bf16 v[80:83], v[178:181], v[206:209], v[80:83]
	v_mfma_f32_16x16x32_bf16 v[72:75], v[170:173], v[214:217], v[72:75]
	v_mfma_f32_16x16x32_bf16 v[64:67], v[178:181], v[214:217], v[64:67]
	s_setprio 0
	s_barrier
	s_add_i32 s28, s55, s36
	v_lshl_add_u64 v[198:199], v[198:199], 0, s[8:9]
	s_mov_b32 m0, s28
	ds_read_b128 v[182:185], v149 offset:49152
	ds_read_b128 v[186:189], v149 offset:50176
	ds_read_b128 v[190:193], v149 offset:51200
	ds_read_b128 v[194:197], v149 offset:52224
	ds_read_b128 v[202:205], v149 offset:53248
	ds_read_b128 v[206:209], v149 offset:54272
	ds_read_b128 v[210:213], v149 offset:55296
	ds_read_b128 v[214:217], v149 offset:56320
	global_load_lds_dwordx4 v[198:199], off
	s_add_i32 m0, s28, 0x2000
	s_add_u32 s24, s24, 0x40080
	v_lshl_add_u64 v[198:199], v[200:201], 0, s[8:9]
	s_addc_u32 s25, s25, 0
	s_add_i32 s28, s56, s36
	global_load_lds_dwordx4 v[198:199], off
	v_lshl_add_u64 v[198:199], s[24:25], 0, v[132:133]
	s_mov_b32 m0, s28
	s_nop 0
	global_load_lds_dwordx4 v[198:199], off
	v_lshl_add_u64 v[198:199], s[24:25], 0, v[128:129]
	s_add_i32 m0, s28, 0x2000
	s_nop 0
	global_load_lds_dwordx4 v[198:199], off
	v_lshl_add_u64 v[198:199], v[218:219], 0, s[8:9]
	s_mov_b32 m0, s43
	s_nop 0
	global_load_lds_dwordx4 v[198:199], off
	v_lshl_add_u64 v[198:199], v[220:221], 0, s[8:9]
	s_mov_b32 m0, s44
	s_nop 0
	global_load_lds_dwordx4 v[198:199], off
	s_add_i32 s54, s54, 2
	s_add_u32 s22, s22, 0x100
	s_addc_u32 s23, s23, 0
	s_add_u32 s52, s52, 0x100
	s_addc_u32 s53, s53, 0
	s_cmp_gt_u32 s54, 13
	s_waitcnt vmcnt(8)
	s_waitcnt lgkmcnt(0)
	s_barrier
	s_setprio 1
	s_waitcnt lgkmcnt(0)
	v_mfma_f32_16x16x32_bf16 v[60:63], v[150:153], v[182:185], v[60:63]
	v_mfma_f32_16x16x32_bf16 v[52:55], v[158:161], v[182:185], v[52:55]
	v_mfma_f32_16x16x32_bf16 v[44:47], v[150:153], v[190:193], v[44:47]
	v_mfma_f32_16x16x32_bf16 v[36:39], v[158:161], v[190:193], v[36:39]
	v_mfma_f32_16x16x32_bf16 v[28:31], v[150:153], v[202:205], v[28:31]
	v_mfma_f32_16x16x32_bf16 v[20:23], v[158:161], v[202:205], v[20:23]
	v_mfma_f32_16x16x32_bf16 v[12:15], v[150:153], v[210:213], v[12:15]
	v_mfma_f32_16x16x32_bf16 v[4:7], v[158:161], v[210:213], v[4:7]
	v_mfma_f32_16x16x32_bf16 v[60:63], v[154:157], v[186:189], v[60:63]
	v_mfma_f32_16x16x32_bf16 v[52:55], v[162:165], v[186:189], v[52:55]
	v_mfma_f32_16x16x32_bf16 v[44:47], v[154:157], v[194:197], v[44:47]
	v_mfma_f32_16x16x32_bf16 v[36:39], v[162:165], v[194:197], v[36:39]
	v_mfma_f32_16x16x32_bf16 v[28:31], v[154:157], v[206:209], v[28:31]
	v_mfma_f32_16x16x32_bf16 v[20:23], v[162:165], v[206:209], v[20:23]
	v_mfma_f32_16x16x32_bf16 v[12:15], v[154:157], v[214:217], v[12:15]
	v_mfma_f32_16x16x32_bf16 v[4:7], v[162:165], v[214:217], v[4:7]
	s_setprio 0
	s_setprio 1
	v_mfma_f32_16x16x32_bf16 v[56:59], v[166:169], v[182:185], v[56:59]
	v_mfma_f32_16x16x32_bf16 v[48:51], v[174:177], v[182:185], v[48:51]
	v_mfma_f32_16x16x32_bf16 v[40:43], v[166:169], v[190:193], v[40:43]
	v_mfma_f32_16x16x32_bf16 v[32:35], v[174:177], v[190:193], v[32:35]
	v_mfma_f32_16x16x32_bf16 v[24:27], v[166:169], v[202:205], v[24:27]
	v_mfma_f32_16x16x32_bf16 v[16:19], v[174:177], v[202:205], v[16:19]
	v_mfma_f32_16x16x32_bf16 v[8:11], v[166:169], v[210:213], v[8:11]
	v_mfma_f32_16x16x32_bf16 v[0:3], v[174:177], v[210:213], v[0:3]
	v_mfma_f32_16x16x32_bf16 v[56:59], v[170:173], v[186:189], v[56:59]
	v_mfma_f32_16x16x32_bf16 v[48:51], v[178:181], v[186:189], v[48:51]
	v_mfma_f32_16x16x32_bf16 v[40:43], v[170:173], v[194:197], v[40:43]
	v_mfma_f32_16x16x32_bf16 v[32:35], v[178:181], v[194:197], v[32:35]
	v_mfma_f32_16x16x32_bf16 v[24:27], v[170:173], v[206:209], v[24:27]
	v_mfma_f32_16x16x32_bf16 v[16:19], v[178:181], v[206:209], v[16:19]
	v_mfma_f32_16x16x32_bf16 v[8:11], v[170:173], v[214:217], v[8:11]
	v_mfma_f32_16x16x32_bf16 v[0:3], v[178:181], v[214:217], v[0:3]
	s_setprio 0
	s_barrier
	s_cbranch_scc0 .LBB0_1308
	s_and_b64 vcc, exec, s[10:11]
	s_cbranch_vccz .LBB0_1311
	s_barrier

.LBB0_1391:
	v_add_u32_e32 v140, s42, v200
	v_add_u32_e32 v203, s43, v200
	ds_read_b128 v[128:131], v140
	ds_read_b128 v[132:135], v140 offset:1024
	ds_read_b128 v[136:139], v140 offset:2048
	ds_read_b128 v[140:143], v140 offset:3072
	ds_read_b128 v[144:147], v203
	ds_read_b128 v[196:199], v203 offset:1024
	ds_read_b128 v[204:207], v203 offset:2048
	ds_read_b128 v[208:211], v203 offset:3072
	s_add_u32 s14, s12, 0x100
	s_addc_u32 s15, s13, 0
	s_cmp_eq_u32 s49, 40
	s_cselect_b32 s19, s3, s15
	s_cselect_b32 s18, s2, s14
	s_cselect_b32 s17, s11, s48
	s_cselect_b32 s16, s10, s47
	v_lshl_add_u64 v[244:245], s[12:13], 0, v[188:189]
	s_add_i32 m0, s28, 0xc000
	ds_read_b128 v[212:215], v202
	ds_read_b128 v[216:219], v202 offset:1024
	ds_read_b128 v[220:223], v202 offset:2048
	ds_read_b128 v[224:227], v202 offset:3072
	ds_read_b128 v[228:231], v202 offset:4096
	ds_read_b128 v[232:235], v202 offset:5120
	ds_read_b128 v[236:239], v202 offset:6144
	ds_read_b128 v[240:243], v202 offset:7168
	global_load_lds_dwordx4 v[244:245], off
	v_lshl_add_u64 v[244:245], s[12:13], 0, v[190:191]
	s_add_i32 m0, s28, 0xe000
	s_nop 0
	global_load_lds_dwordx4 v[244:245], off
	s_waitcnt vmcnt(8)
	s_waitcnt lgkmcnt(0)
	s_barrier
	s_setprio 1
	s_waitcnt lgkmcnt(0)
	v_mfma_f32_16x16x32_bf16 v[124:127], v[128:131], v[212:215], v[124:127]
	v_mfma_f32_16x16x32_bf16 v[120:123], v[136:139], v[212:215], v[120:123]
	v_mfma_f32_16x16x32_bf16 v[116:119], v[128:131], v[220:223], v[116:119]
	v_mfma_f32_16x16x32_bf16 v[112:115], v[136:139], v[220:223], v[112:115]
	v_mfma_f32_16x16x32_bf16 v[92:95], v[128:131], v[228:231], v[92:95]
	v_mfma_f32_16x16x32_bf16 v[88:91], v[136:139], v[228:231], v[88:91]
	v_mfma_f32_16x16x32_bf16 v[80:83], v[128:131], v[236:239], v[80:83]
	v_mfma_f32_16x16x32_bf16 v[72:75], v[136:139], v[236:239], v[72:75]
	v_mfma_f32_16x16x32_bf16 v[124:127], v[132:135], v[216:219], v[124:127]
	v_mfma_f32_16x16x32_bf16 v[120:123], v[140:143], v[216:219], v[120:123]
	v_mfma_f32_16x16x32_bf16 v[116:119], v[132:135], v[224:227], v[116:119]
	v_mfma_f32_16x16x32_bf16 v[112:115], v[140:143], v[224:227], v[112:115]
	v_mfma_f32_16x16x32_bf16 v[92:95], v[132:135], v[232:235], v[92:95]
	v_mfma_f32_16x16x32_bf16 v[88:91], v[140:143], v[232:235], v[88:91]
	v_mfma_f32_16x16x32_bf16 v[80:83], v[132:135], v[240:243], v[80:83]
	v_mfma_f32_16x16x32_bf16 v[72:75], v[140:143], v[240:243], v[72:75]
	s_setprio 0
	s_setprio 1
	v_mfma_f32_16x16x32_bf16 v[108:111], v[144:147], v[212:215], v[108:111]
	v_mfma_f32_16x16x32_bf16 v[104:107], v[204:207], v[212:215], v[104:107]
	v_mfma_f32_16x16x32_bf16 v[100:103], v[144:147], v[220:223], v[100:103]
	v_mfma_f32_16x16x32_bf16 v[96:99], v[204:207], v[220:223], v[96:99]
	v_mfma_f32_16x16x32_bf16 v[84:87], v[144:147], v[228:231], v[84:87]
	v_mfma_f32_16x16x32_bf16 v[76:79], v[204:207], v[228:231], v[76:79]
	v_mfma_f32_16x16x32_bf16 v[68:71], v[144:147], v[236:239], v[68:71]
	v_mfma_f32_16x16x32_bf16 v[64:67], v[204:207], v[236:239], v[64:67]
	v_mfma_f32_16x16x32_bf16 v[108:111], v[196:199], v[216:219], v[108:111]
	v_mfma_f32_16x16x32_bf16 v[104:107], v[208:211], v[216:219], v[104:107]
	v_mfma_f32_16x16x32_bf16 v[100:103], v[196:199], v[224:227], v[100:103]
	v_mfma_f32_16x16x32_bf16 v[96:99], v[208:211], v[224:227], v[96:99]
	v_mfma_f32_16x16x32_bf16 v[84:87], v[196:199], v[232:235], v[84:87]
	v_mfma_f32_16x16x32_bf16 v[76:79], v[208:211], v[232:235], v[76:79]
	v_mfma_f32_16x16x32_bf16 v[68:71], v[196:199], v[240:243], v[68:71]
	v_mfma_f32_16x16x32_bf16 v[64:67], v[208:211], v[240:243], v[64:67]
	s_setprio 0
	s_barrier
	s_add_i32 s12, s42, s25
	v_lshl_add_u64 v[244:245], s[16:17], 0, v[150:151]
	s_mov_b32 m0, s12
	ds_read_b128 v[212:215], v202 offset:16384
	ds_read_b128 v[216:219], v202 offset:17408
	ds_read_b128 v[220:223], v202 offset:18432
	ds_read_b128 v[224:227], v202 offset:19456
	ds_read_b128 v[228:231], v202 offset:20480
	ds_read_b128 v[232:235], v202 offset:21504
	ds_read_b128 v[236:239], v202 offset:22528
	ds_read_b128 v[240:243], v202 offset:23552
	global_load_lds_dwordx4 v[244:245], off
	s_add_i32 m0, s12, 0x2000
	s_add_u32 s12, s16, 0xb0000
	v_lshl_add_u64 v[246:247], s[16:17], 0, v[154:155]
	s_addc_u32 s13, s17, 0
	s_add_i32 s50, s43, s25
	global_load_lds_dwordx4 v[246:247], off
	v_lshl_add_u64 v[248:249], s[12:13], 0, v[150:151]
	s_mov_b32 m0, s50
	v_lshl_add_u64 v[250:251], s[18:19], 0, v[152:153]
	global_load_lds_dwordx4 v[248:249], off
	v_lshl_add_u64 v[248:249], s[12:13], 0, v[154:155]
	s_add_i32 m0, s50, 0x2000
	s_nop 0
	global_load_lds_dwordx4 v[248:249], off
	v_lshl_add_u64 v[248:249], s[18:19], 0, v[148:149]
	s_mov_b32 m0, s28
	s_nop 0
	global_load_lds_dwordx4 v[248:249], off
	s_mov_b32 m0, s29
	s_nop 0
	global_load_lds_dwordx4 v[250:251], off
	s_waitcnt vmcnt(8)
	s_waitcnt lgkmcnt(0)
	s_barrier
	s_setprio 1
	s_waitcnt lgkmcnt(0)
	v_mfma_f32_16x16x32_bf16 v[60:63], v[128:131], v[212:215], v[60:63]
	v_mfma_f32_16x16x32_bf16 v[56:59], v[136:139], v[212:215], v[56:59]
	v_mfma_f32_16x16x32_bf16 v[48:51], v[128:131], v[220:223], v[48:51]
	v_mfma_f32_16x16x32_bf16 v[40:43], v[136:139], v[220:223], v[40:43]
	v_mfma_f32_16x16x32_bf16 v[32:35], v[128:131], v[228:231], v[32:35]
	v_mfma_f32_16x16x32_bf16 v[24:27], v[136:139], v[228:231], v[24:27]
	v_mfma_f32_16x16x32_bf16 v[16:19], v[128:131], v[236:239], v[16:19]
	v_mfma_f32_16x16x32_bf16 v[8:11], v[136:139], v[236:239], v[8:11]
	v_mfma_f32_16x16x32_bf16 v[60:63], v[132:135], v[216:219], v[60:63]
	v_mfma_f32_16x16x32_bf16 v[56:59], v[140:143], v[216:219], v[56:59]
	v_mfma_f32_16x16x32_bf16 v[48:51], v[132:135], v[224:227], v[48:51]
	v_mfma_f32_16x16x32_bf16 v[40:43], v[140:143], v[224:227], v[40:43]
	v_mfma_f32_16x16x32_bf16 v[32:35], v[132:135], v[232:235], v[32:35]
	v_mfma_f32_16x16x32_bf16 v[24:27], v[140:143], v[232:235], v[24:27]
	v_mfma_f32_16x16x32_bf16 v[16:19], v[132:135], v[240:243], v[16:19]
	v_mfma_f32_16x16x32_bf16 v[8:11], v[140:143], v[240:243], v[8:11]
	s_setprio 0
	s_setprio 1
	v_mfma_f32_16x16x32_bf16 v[52:55], v[144:147], v[212:215], v[52:55]
	v_mfma_f32_16x16x32_bf16 v[44:47], v[204:207], v[212:215], v[44:47]
	v_mfma_f32_16x16x32_bf16 v[36:39], v[144:147], v[220:223], v[36:39]
	v_mfma_f32_16x16x32_bf16 v[28:31], v[204:207], v[220:223], v[28:31]
	v_mfma_f32_16x16x32_bf16 v[20:23], v[144:147], v[228:231], v[20:23]
	v_mfma_f32_16x16x32_bf16 v[12:15], v[204:207], v[228:231], v[12:15]
	v_mfma_f32_16x16x32_bf16 v[4:7], v[144:147], v[236:239], v[4:7]
	v_mfma_f32_16x16x32_bf16 v[0:3], v[204:207], v[236:239], v[0:3]
	v_mfma_f32_16x16x32_bf16 v[52:55], v[196:199], v[216:219], v[52:55]
	v_mfma_f32_16x16x32_bf16 v[44:47], v[208:211], v[216:219], v[44:47]
	v_mfma_f32_16x16x32_bf16 v[36:39], v[196:199], v[224:227], v[36:39]
	v_mfma_f32_16x16x32_bf16 v[28:31], v[208:211], v[224:227], v[28:31]
	v_mfma_f32_16x16x32_bf16 v[20:23], v[196:199], v[232:235], v[20:23]
	v_mfma_f32_16x16x32_bf16 v[12:15], v[208:211], v[232:235], v[12:15]
	v_mfma_f32_16x16x32_bf16 v[4:7], v[196:199], v[240:243], v[4:7]
	v_mfma_f32_16x16x32_bf16 v[0:3], v[208:211], v[240:243], v[0:3]
	s_setprio 0
	s_barrier
	s_add_i32 s50, 0, 0x18000
	s_add_i32 s51, 0, 0x1c000
	v_add_u32_e32 v140, s50, v200
	v_add_u32_e32 v203, s51, v200
	ds_read_b128 v[128:131], v140
	ds_read_b128 v[132:135], v140 offset:1024
	ds_read_b128 v[136:139], v140 offset:2048
	ds_read_b128 v[140:143], v140 offset:3072
	ds_read_b128 v[144:147], v203
	ds_read_b128 v[196:199], v203 offset:1024
	ds_read_b128 v[204:207], v203 offset:2048
	ds_read_b128 v[208:211], v203 offset:3072
	s_add_u32 s12, s18, 0xb0000
	s_addc_u32 s13, s19, 0
	s_mov_b32 m0, s30
	v_lshl_add_u64 v[252:253], s[12:13], 0, v[148:149]
	ds_read_b128 v[212:215], v202 offset:32768
	ds_read_b128 v[216:219], v202 offset:33792
	ds_read_b128 v[220:223], v202 offset:34816
	ds_read_b128 v[224:227], v202 offset:35840
	ds_read_b128 v[228:231], v202 offset:36864
	ds_read_b128 v[232:235], v202 offset:37888
	ds_read_b128 v[236:239], v202 offset:38912
	ds_read_b128 v[240:243], v202 offset:39936
	global_load_lds_dwordx4 v[252:253], off
	v_lshl_add_u64 v[252:253], s[12:13], 0, v[152:153]
	s_mov_b32 m0, s31
	s_nop 0
	global_load_lds_dwordx4 v[252:253], off
	s_waitcnt vmcnt(8)
	s_waitcnt lgkmcnt(0)
	s_barrier
	s_setprio 1
	s_waitcnt lgkmcnt(0)
	v_mfma_f32_16x16x32_bf16 v[124:127], v[128:131], v[212:215], v[124:127]
	v_mfma_f32_16x16x32_bf16 v[120:123], v[136:139], v[212:215], v[120:123]
	v_mfma_f32_16x16x32_bf16 v[116:119], v[128:131], v[220:223], v[116:119]
	v_mfma_f32_16x16x32_bf16 v[112:115], v[136:139], v[220:223], v[112:115]
	v_mfma_f32_16x16x32_bf16 v[92:95], v[128:131], v[228:231], v[92:95]
	v_mfma_f32_16x16x32_bf16 v[88:91], v[136:139], v[228:231], v[88:91]
	v_mfma_f32_16x16x32_bf16 v[80:83], v[128:131], v[236:239], v[80:83]
	v_mfma_f32_16x16x32_bf16 v[72:75], v[136:139], v[236:239], v[72:75]
	v_mfma_f32_16x16x32_bf16 v[124:127], v[132:135], v[216:219], v[124:127]
	v_mfma_f32_16x16x32_bf16 v[120:123], v[140:143], v[216:219], v[120:123]
	v_mfma_f32_16x16x32_bf16 v[116:119], v[132:135], v[224:227], v[116:119]
	v_mfma_f32_16x16x32_bf16 v[112:115], v[140:143], v[224:227], v[112:115]
	v_mfma_f32_16x16x32_bf16 v[92:95], v[132:135], v[232:235], v[92:95]
	v_mfma_f32_16x16x32_bf16 v[88:91], v[140:143], v[232:235], v[88:91]
	v_mfma_f32_16x16x32_bf16 v[80:83], v[132:135], v[240:243], v[80:83]
	v_mfma_f32_16x16x32_bf16 v[72:75], v[140:143], v[240:243], v[72:75]
	s_setprio 0
	s_setprio 1
	v_mfma_f32_16x16x32_bf16 v[108:111], v[144:147], v[212:215], v[108:111]
	v_mfma_f32_16x16x32_bf16 v[104:107], v[204:207], v[212:215], v[104:107]
	v_mfma_f32_16x16x32_bf16 v[100:103], v[144:147], v[220:223], v[100:103]
	v_mfma_f32_16x16x32_bf16 v[96:99], v[204:207], v[220:223], v[96:99]
	v_mfma_f32_16x16x32_bf16 v[84:87], v[144:147], v[228:231], v[84:87]
	v_mfma_f32_16x16x32_bf16 v[76:79], v[204:207], v[228:231], v[76:79]
	v_mfma_f32_16x16x32_bf16 v[68:71], v[144:147], v[236:239], v[68:71]
	v_mfma_f32_16x16x32_bf16 v[64:67], v[204:207], v[236:239], v[64:67]
	v_mfma_f32_16x16x32_bf16 v[108:111], v[196:199], v[216:219], v[108:111]
	v_mfma_f32_16x16x32_bf16 v[104:107], v[208:211], v[216:219], v[104:107]
	v_mfma_f32_16x16x32_bf16 v[100:103], v[196:199], v[224:227], v[100:103]
	v_mfma_f32_16x16x32_bf16 v[96:99], v[208:211], v[224:227], v[96:99]
	v_mfma_f32_16x16x32_bf16 v[84:87], v[196:199], v[232:235], v[84:87]
	v_mfma_f32_16x16x32_bf16 v[76:79], v[208:211], v[232:235], v[76:79]
	v_mfma_f32_16x16x32_bf16 v[68:71], v[196:199], v[240:243], v[68:71]
	v_mfma_f32_16x16x32_bf16 v[64:67], v[208:211], v[240:243], v[64:67]
	s_setprio 0
	s_barrier
	s_add_i32 s12, s50, s25
	v_lshl_add_u64 v[244:245], v[244:245], 0, s[6:7]
	s_mov_b32 m0, s12
	ds_read_b128 v[212:215], v202 offset:49152
	ds_read_b128 v[216:219], v202 offset:50176
	ds_read_b128 v[220:223], v202 offset:51200
	ds_read_b128 v[224:227], v202 offset:52224
	ds_read_b128 v[228:231], v202 offset:53248
	ds_read_b128 v[232:235], v202 offset:54272
	ds_read_b128 v[236:239], v202 offset:55296
	ds_read_b128 v[240:243], v202 offset:56320
	global_load_lds_dwordx4 v[244:245], off
	s_add_i32 m0, s12, 0x2000
	s_add_u32 s12, s16, 0xb0080
	v_lshl_add_u64 v[244:245], v[246:247], 0, s[6:7]
	s_addc_u32 s13, s17, 0
	s_add_i32 s16, s51, s25
	global_load_lds_dwordx4 v[244:245], off
	v_lshl_add_u64 v[244:245], s[12:13], 0, v[150:151]
	s_mov_b32 m0, s16
	s_nop 0
	global_load_lds_dwordx4 v[244:245], off
	v_lshl_add_u64 v[244:245], s[12:13], 0, v[154:155]
	s_add_i32 m0, s16, 0x2000
	s_nop 0
	global_load_lds_dwordx4 v[244:245], off
	v_lshl_add_u64 v[244:245], v[248:249], 0, s[6:7]
	s_mov_b32 m0, s39
	s_nop 0
	global_load_lds_dwordx4 v[244:245], off
	v_lshl_add_u64 v[244:245], v[250:251], 0, s[6:7]
	s_mov_b32 m0, s40
	s_nop 0
	global_load_lds_dwordx4 v[244:245], off
	s_add_i32 s49, s49, 2
	s_add_u32 s47, s47, 0x100
	s_addc_u32 s48, s48, 0
	s_cmp_gt_u32 s49, 41
	s_mov_b64 s[12:13], s[14:15]
	s_waitcnt vmcnt(8)
	s_waitcnt lgkmcnt(0)
	s_barrier
	s_setprio 1
	s_waitcnt lgkmcnt(0)
	v_mfma_f32_16x16x32_bf16 v[60:63], v[128:131], v[212:215], v[60:63]
	v_mfma_f32_16x16x32_bf16 v[56:59], v[136:139], v[212:215], v[56:59]
	v_mfma_f32_16x16x32_bf16 v[48:51], v[128:131], v[220:223], v[48:51]
	v_mfma_f32_16x16x32_bf16 v[40:43], v[136:139], v[220:223], v[40:43]
	v_mfma_f32_16x16x32_bf16 v[32:35], v[128:131], v[228:231], v[32:35]
	v_mfma_f32_16x16x32_bf16 v[24:27], v[136:139], v[228:231], v[24:27]
	v_mfma_f32_16x16x32_bf16 v[16:19], v[128:131], v[236:239], v[16:19]
	v_mfma_f32_16x16x32_bf16 v[8:11], v[136:139], v[236:239], v[8:11]
	v_mfma_f32_16x16x32_bf16 v[60:63], v[132:135], v[216:219], v[60:63]
	v_mfma_f32_16x16x32_bf16 v[56:59], v[140:143], v[216:219], v[56:59]
	v_mfma_f32_16x16x32_bf16 v[48:51], v[132:135], v[224:227], v[48:51]
	v_mfma_f32_16x16x32_bf16 v[40:43], v[140:143], v[224:227], v[40:43]
	v_mfma_f32_16x16x32_bf16 v[32:35], v[132:135], v[232:235], v[32:35]
	v_mfma_f32_16x16x32_bf16 v[24:27], v[140:143], v[232:235], v[24:27]
	v_mfma_f32_16x16x32_bf16 v[16:19], v[132:135], v[240:243], v[16:19]
	v_mfma_f32_16x16x32_bf16 v[8:11], v[140:143], v[240:243], v[8:11]
	s_setprio 0
	s_setprio 1
	v_mfma_f32_16x16x32_bf16 v[52:55], v[144:147], v[212:215], v[52:55]
	v_mfma_f32_16x16x32_bf16 v[44:47], v[204:207], v[212:215], v[44:47]
	v_mfma_f32_16x16x32_bf16 v[36:39], v[144:147], v[220:223], v[36:39]
	v_mfma_f32_16x16x32_bf16 v[28:31], v[204:207], v[220:223], v[28:31]
	v_mfma_f32_16x16x32_bf16 v[20:23], v[144:147], v[228:231], v[20:23]
	v_mfma_f32_16x16x32_bf16 v[12:15], v[204:207], v[228:231], v[12:15]
	v_mfma_f32_16x16x32_bf16 v[4:7], v[144:147], v[236:239], v[4:7]
	v_mfma_f32_16x16x32_bf16 v[0:3], v[204:207], v[236:239], v[0:3]
	v_mfma_f32_16x16x32_bf16 v[52:55], v[196:199], v[216:219], v[52:55]
	v_mfma_f32_16x16x32_bf16 v[44:47], v[208:211], v[216:219], v[44:47]
	v_mfma_f32_16x16x32_bf16 v[36:39], v[196:199], v[224:227], v[36:39]
	v_mfma_f32_16x16x32_bf16 v[28:31], v[208:211], v[224:227], v[28:31]
	v_mfma_f32_16x16x32_bf16 v[20:23], v[196:199], v[232:235], v[20:23]
	v_mfma_f32_16x16x32_bf16 v[12:15], v[208:211], v[232:235], v[12:15]
	v_mfma_f32_16x16x32_bf16 v[4:7], v[196:199], v[240:243], v[4:7]
	v_mfma_f32_16x16x32_bf16 v[0:3], v[208:211], v[240:243], v[0:3]
	s_setprio 0
	s_barrier
	s_cbranch_scc0 .LBB0_1391
	s_and_b64 vcc, exec, s[8:9]
	s_cbranch_vccz .LBB0_1394
	s_barrier
